# attention: -B2 folded into QK accumulator init (32 fewer VALU per tile); 8x4 K-loops: scalar-base (saddr) LDS-DMA with captured 32-bit lane offsets
# speedup vs baseline: 1.0943x; 1.0167x over previous
; #define LDB_(dst, ks) _Pragma("unroll") for (int n = 0; n < 4; ++n) dst[n] = *(const bf16x8*)(sB + b_off + n * 2048 + (ks) * 1024)
; #define LDA_(dst, ks, h) _Pragma("unroll") for (int m = 0; m < 4; ++m) dst[m] = *(const bf16x8*)(sA + a_off + ((h) * 4 + m) * 2048 + (ks) * 1024)
; #define MMA_(A, B, h) _Pragma("unroll") for (int m = 0; m < 4; ++m) _Pragma("unroll") for (int n = 0; n < 4; ++n) \
;       acc[(h) * 4 + m][n] = SWAP ? MFMA16(B[n], A[m], acc[(h) * 4 + m][n]) : MFMA16(A[m], B[n], acc[(h) * 4 + m][n])
; template <int MF, int NF, bool SWAP = true>
; DI void gemm_main(f32x4 (&acc)[MF][NF], const u16* __restrict__ Ab, int lda, const u16* __restrict__ Bb, int ldb,
;                   int K, char* shm) {
;     ...
;   for (int t = 0; t < nt; ++t) {
;     const int cur = RING3 ? cur3 : (t & 1);
;     if constexpr (RING3) {
;       if (t + 2 < nt) G_STAGE(nxt3, t + 2);
;     } else {
;       if (t + 1 < nt) G_STAGE(cur ^ 1, t + 1);
;     ...
;     if constexpr (MF == 8 && NF == 4) {
;       bf16x8 B0[4], B1[4], A0[4], A1[4], A2[4], A3[4];
;     ...
;       LDB_(B0, 0); LDA_(A0, 0, 0);
;       LDA_(A1, 0, 1); MMA_(A0, B0, 0);
;       LDB_(B1, 1); LDA_(A2, 1, 0); MMA_(A1, B0, 1);
;       LDA_(A3, 1, 1); MMA_(A2, B1, 0);
;       MMA_(A3, B1, 1);
;     ...
;       __builtin_amdgcn_sched_group_barrier(0x100, 8, 0);
; #pragma unroll
;       for (int i = 0; i < 4; ++i) { __builtin_amdgcn_sched_group_barrier(0x100, 1, 0); __builtin_amdgcn_sched_group_barrier(0x008, 4, 0); }
; #pragma unroll
;       for (int i = 0; i < 8; ++i) { __builtin_amdgcn_sched_group_barrier(0x100, 1, 0); __builtin_amdgcn_sched_group_barrier(0x008, 2, 0); }
; #pragma unroll
;       for (int i = 0; i < 4; ++i) { __builtin_amdgcn_sched_group_barrier(0x100, 1, 0); __builtin_amdgcn_sched_group_barrier(0x008, 4, 0); }
;       __builtin_amdgcn_sched_group_barrier(0x008, 16, 0);
;       __builtin_amdgcn_sched_barrier(0);
.LBB0_146:
	s_and_b32 s19, s17, 0x10000
	v_add_u32_e32 v137, s19, v132
	v_add_u32_e32 v178, v137, v131
	ds_read_b128 v[138:141], v178 offset:32768
	ds_read_b128 v[142:145], v178 offset:34816
	ds_read_b128 v[146:149], v178 offset:36864
	ds_read_b128 v[150:153], v178 offset:38912
	v_add_u32_e32 v137, v137, v129
	ds_read_b128 v[154:157], v137
	ds_read_b128 v[158:161], v137 offset:2048
	ds_read_b128 v[162:165], v137 offset:4096
	ds_read_b128 v[166:169], v137 offset:6144
	ds_read_b128 v[170:173], v137 offset:8192
	s_cmp_gt_u32 s13, 14
	s_cbranch_scc1 .Lg_rot146_last
	s_cmp_eq_u32 s13, 0
	s_cbranch_scc1 .Lg_rot146_first
	v_mfma_f32_16x16x32_bf16 v[60:63], v[186:189], v[190:193], v[60:63]
	s_xor_b32 s20, s19, 0x10000
	v_add_u32_e32 v179, s20, v128
	v_mfma_f32_16x16x32_bf16 v[56:59], v[194:197], v[190:193], v[56:59]
	s_nop 0
	v_readfirstlane_b32 s20, v179
	s_nop 1
	s_add_u32 m0, s20, 0x0
	v_mfma_f32_16x16x32_bf16 v[52:55], v[198:201], v[190:193], v[52:55]
	global_load_lds_dwordx4 v251, s[98:99]
	s_add_u32 m0, s20, 0x2000
	v_mfma_f32_16x16x32_bf16 v[48:51], v[212:215], v[190:193], v[48:51]
	global_load_lds_dwordx4 v250, s[98:99]
	s_add_u32 m0, s20, 0x4000
	v_mfma_f32_16x16x32_bf16 v[44:47], v[186:189], v[216:219], v[44:47]
	global_load_lds_dwordx4 v249, s[98:99]
	s_add_u32 m0, s20, 0x6000
	v_mfma_f32_16x16x32_bf16 v[40:43], v[194:197], v[216:219], v[40:43]
	global_load_lds_dwordx4 v248, s[98:99]
	s_add_u32 m0, s20, 0x8000
	v_mfma_f32_16x16x32_bf16 v[36:39], v[198:201], v[216:219], v[36:39]
	global_load_lds_dwordx4 v247, s[100:101]
	s_add_u32 m0, s20, 0xa000
	v_mfma_f32_16x16x32_bf16 v[32:35], v[212:215], v[216:219], v[32:35]
	global_load_lds_dwordx4 v246, s[100:101]
	s_add_u32 m0, s20, 0xc000
	v_mfma_f32_16x16x32_bf16 v[28:31], v[186:189], v[220:223], v[28:31]
	global_load_lds_dwordx4 v245, s[100:101]
	s_add_u32 m0, s20, 0xe000
	v_mfma_f32_16x16x32_bf16 v[24:27], v[194:197], v[220:223], v[24:27]
	global_load_lds_dwordx4 v244, s[100:101]
	v_mfma_f32_16x16x32_bf16 v[20:23], v[198:201], v[220:223], v[20:23]
	s_add_u32 s98, s98, 0x80
	s_addc_u32 s99, s99, 0
	s_add_u32 s100, s100, 0x80
	s_addc_u32 s101, s101, 0
	v_mfma_f32_16x16x32_bf16 v[16:19], v[212:215], v[220:223], v[16:19]
	v_mfma_f32_16x16x32_bf16 v[12:15], v[186:189], v[224:227], v[12:15]
	v_mfma_f32_16x16x32_bf16 v[8:11], v[194:197], v[224:227], v[8:11]
	v_mfma_f32_16x16x32_bf16 v[4:7], v[198:201], v[224:227], v[4:7]
	v_mfma_f32_16x16x32_bf16 v[0:3], v[212:215], v[224:227], v[0:3]
	s_branch .Lg_rot146_main
.Lg_rot146_first:
	v_add_u32_e32 v174, s11, v136
	s_xor_b32 s20, s19, 0x10000
	v_add_u32_e32 v176, 64, v174
	v_add_u32_e32 v179, s20, v128
	v_ashrrev_i32_e32 v177, 31, v176
	v_lshlrev_b64 v[176:177], 1, v[176:177]
	v_readfirstlane_b32 s20, v179
	v_lshl_add_u64 v[180:181], s[0:1], 0, v[176:177]
	s_mov_b32 m0, s20
	v_add_u32_e32 v182, 0x2000, v179
	global_load_lds_dwordx4 v[180:181], off
	v_subrev_u32_e32 v251, s0, v180
	v_add_u32_e32 v180, 0x10040, v174
	v_ashrrev_i32_e32 v181, 31, v180
	v_lshlrev_b64 v[180:181], 1, v[180:181]
	v_readfirstlane_b32 s20, v182
	v_lshl_add_u64 v[184:185], s[0:1], 0, v[180:181]
	s_mov_b32 m0, s20
	v_add_u32_e32 v175, 0x4000, v179
	global_load_lds_dwordx4 v[184:185], off
	v_subrev_u32_e32 v250, s0, v184
	v_add_u32_e32 v184, 0x20040, v174
	v_ashrrev_i32_e32 v185, 31, v184
	v_lshlrev_b64 v[184:185], 1, v[184:185]
	v_readfirstlane_b32 s20, v175
	v_lshl_add_u64 v[182:183], s[0:1], 0, v[184:185]
	s_mov_b32 m0, s20
	v_add_u32_e32 v211, 0x6000, v179
	global_load_lds_dwordx4 v[182:183], off
	v_subrev_u32_e32 v249, s0, v182
	v_add_u32_e32 v182, 0x30040, v174
	v_ashrrev_i32_e32 v183, 31, v182
	v_lshlrev_b64 v[182:183], 1, v[182:183]
	v_readfirstlane_b32 s20, v211
	v_lshl_add_u64 v[174:175], s[0:1], 0, v[182:183]
	s_mov_b32 m0, s20
	v_lshl_add_u64 v[176:177], s[4:5], 0, v[176:177]
	global_load_lds_dwordx4 v[174:175], off
	v_subrev_u32_e32 v248, s0, v174
	v_add_u32_e32 v174, 0x8000, v179
	s_nop 0
	v_readfirstlane_b32 s20, v174
	s_mov_b32 m0, s20
	s_nop 0
	global_load_lds_dwordx4 v[176:177], off
	v_subrev_u32_e32 v247, s4, v176
	v_lshl_add_u64 v[176:177], s[4:5], 0, v[180:181]
	v_add_u32_e32 v180, 0xa000, v179
	s_nop 0
	v_readfirstlane_b32 s20, v180
	v_add_u32_e32 v180, 0xc000, v179
	s_mov_b32 m0, s20
	v_readfirstlane_b32 s20, v180
	v_add_u32_e32 v179, 0xe000, v179
	global_load_lds_dwordx4 v[176:177], off
	v_subrev_u32_e32 v246, s4, v176
	v_lshl_add_u64 v[176:177], s[4:5], 0, v[184:185]
	s_mov_b32 m0, s20
	v_readfirstlane_b32 s20, v179
	global_load_lds_dwordx4 v[176:177], off
	v_subrev_u32_e32 v245, s4, v176
	v_lshl_add_u64 v[176:177], s[4:5], 0, v[182:183]
	s_mov_b32 m0, s20
	s_nop 0
	global_load_lds_dwordx4 v[176:177], off
	v_subrev_u32_e32 v244, s4, v176
	s_add_u32 s98, s0, 0x80
	s_addc_u32 s99, s1, 0
	s_add_u32 s100, s4, 0x80
	s_addc_u32 s101, s5, 0
	s_branch .Lg_rot146_main

; #define LDB_(dst, ks) _Pragma("unroll") for (int n = 0; n < 4; ++n) dst[n] = *(const bf16x8*)(sB + b_off + n * 2048 + (ks) * 1024)
; #define LDA_(dst, ks, h) _Pragma("unroll") for (int m = 0; m < 4; ++m) dst[m] = *(const bf16x8*)(sA + a_off + ((h) * 4 + m) * 2048 + (ks) * 1024)
; #define MMA_(A, B, h) _Pragma("unroll") for (int m = 0; m < 4; ++m) _Pragma("unroll") for (int n = 0; n < 4; ++n) \
;       acc[(h) * 4 + m][n] = SWAP ? MFMA16(B[n], A[m], acc[(h) * 4 + m][n]) : MFMA16(A[m], B[n], acc[(h) * 4 + m][n])
; template <int MF, int NF, bool SWAP = true>
; DI void gemm_main(f32x4 (&acc)[MF][NF], const u16* __restrict__ Ab, int lda, const u16* __restrict__ Bb, int ldb,
;                   int K, char* shm) {
;     ...
;   for (int t = 0; t < nt; ++t) {
;     const int cur = RING3 ? cur3 : (t & 1);
;     if constexpr (RING3) {
;       if (t + 2 < nt) G_STAGE(nxt3, t + 2);
;     } else {
;       if (t + 1 < nt) G_STAGE(cur ^ 1, t + 1);
;     ...
;     if constexpr (MF == 8 && NF == 4) {
;       bf16x8 B0[4], B1[4], A0[4], A1[4], A2[4], A3[4];
;     ...
;       LDB_(B0, 0); LDA_(A0, 0, 0);
;       LDA_(A1, 0, 1); MMA_(A0, B0, 0);
;       LDB_(B1, 1); LDA_(A2, 1, 0); MMA_(A1, B0, 1);
;       LDA_(A3, 1, 1); MMA_(A2, B1, 0);
;       MMA_(A3, B1, 1);
;     ...
;       __builtin_amdgcn_sched_group_barrier(0x100, 8, 0);
; #pragma unroll
;       for (int i = 0; i < 4; ++i) { __builtin_amdgcn_sched_group_barrier(0x100, 1, 0); __builtin_amdgcn_sched_group_barrier(0x008, 4, 0); }
; #pragma unroll
;       for (int i = 0; i < 8; ++i) { __builtin_amdgcn_sched_group_barrier(0x100, 1, 0); __builtin_amdgcn_sched_group_barrier(0x008, 2, 0); }
; #pragma unroll
;       for (int i = 0; i < 4; ++i) { __builtin_amdgcn_sched_group_barrier(0x100, 1, 0); __builtin_amdgcn_sched_group_barrier(0x008, 4, 0); }
;       __builtin_amdgcn_sched_group_barrier(0x008, 16, 0);
;       __builtin_amdgcn_sched_barrier(0);
.LBB0_244:
	s_and_b32 s18, s15, 0x10000
	v_add_u32_e32 v154, s18, v136
	v_add_u32_e32 v178, v154, v132
	ds_read_b128 v[138:141], v178 offset:32768
	ds_read_b128 v[142:145], v178 offset:34816
	ds_read_b128 v[146:149], v178 offset:36864
	ds_read_b128 v[150:153], v178 offset:38912
	v_add_u32_e32 v186, v154, v129
	ds_read_b128 v[154:157], v186
	ds_read_b128 v[158:161], v186 offset:2048
	ds_read_b128 v[162:165], v186 offset:4096
	ds_read_b128 v[166:169], v186 offset:6144
	ds_read_b128 v[170:173], v186 offset:8192
	s_cmp_gt_u32 s17, 14
	s_cbranch_scc1 .Lg_rot244_last
	s_cmp_eq_u32 s17, 0
	s_cbranch_scc1 .Lg_rot244_first
	v_mfma_f32_16x16x32_bf16 v[60:63], v[188:191], v[192:195], v[60:63]
	s_xor_b32 s19, s18, 0x10000
	v_add_u32_e32 v179, s19, v128
	v_mfma_f32_16x16x32_bf16 v[56:59], v[196:199], v[192:195], v[56:59]
	s_nop 0
	v_readfirstlane_b32 s19, v179
	s_nop 1
	s_add_u32 m0, s19, 0x0
	v_mfma_f32_16x16x32_bf16 v[52:55], v[212:215], v[192:195], v[52:55]
	global_load_lds_dwordx4 v251, s[98:99]
	s_add_u32 m0, s19, 0x2000
	v_mfma_f32_16x16x32_bf16 v[48:51], v[216:219], v[192:195], v[48:51]
	global_load_lds_dwordx4 v250, s[98:99]
	s_add_u32 m0, s19, 0x4000
	v_mfma_f32_16x16x32_bf16 v[44:47], v[188:191], v[220:223], v[44:47]
	global_load_lds_dwordx4 v249, s[98:99]
	s_add_u32 m0, s19, 0x6000
	v_mfma_f32_16x16x32_bf16 v[40:43], v[196:199], v[220:223], v[40:43]
	global_load_lds_dwordx4 v248, s[98:99]
	s_add_u32 m0, s19, 0x8000
	v_mfma_f32_16x16x32_bf16 v[36:39], v[212:215], v[220:223], v[36:39]
	global_load_lds_dwordx4 v247, s[100:101]
	s_add_u32 m0, s19, 0xa000
	v_mfma_f32_16x16x32_bf16 v[32:35], v[216:219], v[220:223], v[32:35]
	global_load_lds_dwordx4 v246, s[100:101]
	s_add_u32 m0, s19, 0xc000
	v_mfma_f32_16x16x32_bf16 v[28:31], v[188:191], v[224:227], v[28:31]
	global_load_lds_dwordx4 v245, s[100:101]
	s_add_u32 m0, s19, 0xe000
	v_mfma_f32_16x16x32_bf16 v[24:27], v[196:199], v[224:227], v[24:27]
	global_load_lds_dwordx4 v244, s[100:101]
	v_mfma_f32_16x16x32_bf16 v[20:23], v[212:215], v[224:227], v[20:23]
	s_add_u32 s98, s98, 0x80
	s_addc_u32 s99, s99, 0
	s_add_u32 s100, s100, 0x80
	s_addc_u32 s101, s101, 0
	v_mfma_f32_16x16x32_bf16 v[16:19], v[216:219], v[224:227], v[16:19]
	v_mfma_f32_16x16x32_bf16 v[12:15], v[188:191], v[228:231], v[12:15]
	v_mfma_f32_16x16x32_bf16 v[8:11], v[196:199], v[228:231], v[8:11]
	v_mfma_f32_16x16x32_bf16 v[4:7], v[212:215], v[228:231], v[4:7]
	v_mfma_f32_16x16x32_bf16 v[0:3], v[216:219], v[228:231], v[0:3]
	s_branch .Lg_rot244_main
.Lg_rot244_first:
	v_add_u32_e32 v174, s16, v137
	s_xor_b32 s19, s18, 0x10000
	v_add_u32_e32 v176, 64, v174
	v_add_u32_e32 v179, s19, v128
	v_ashrrev_i32_e32 v177, 31, v176
	v_lshlrev_b64 v[176:177], 1, v[176:177]
	v_readfirstlane_b32 s19, v179
	v_lshl_add_u64 v[180:181], s[6:7], 0, v[176:177]
	s_mov_b32 m0, s19
	v_add_u32_e32 v182, 0x2000, v179
	global_load_lds_dwordx4 v[180:181], off
	v_subrev_u32_e32 v251, s6, v180
	v_add_u32_e32 v180, 0x10040, v174
	v_ashrrev_i32_e32 v181, 31, v180
	v_lshlrev_b64 v[180:181], 1, v[180:181]
	v_readfirstlane_b32 s19, v182
	v_lshl_add_u64 v[184:185], s[6:7], 0, v[180:181]
	s_mov_b32 m0, s19
	v_add_u32_e32 v175, 0x4000, v179
	global_load_lds_dwordx4 v[184:185], off
	v_subrev_u32_e32 v250, s6, v184
	v_add_u32_e32 v184, 0x20040, v174
	v_ashrrev_i32_e32 v185, 31, v184
	v_lshlrev_b64 v[184:185], 1, v[184:185]
	v_readfirstlane_b32 s19, v175
	v_lshl_add_u64 v[182:183], s[6:7], 0, v[184:185]
	s_mov_b32 m0, s19
	v_add_u32_e32 v187, 0x6000, v179
	global_load_lds_dwordx4 v[182:183], off
	v_subrev_u32_e32 v249, s6, v182
	v_add_u32_e32 v182, 0x30040, v174
	v_ashrrev_i32_e32 v183, 31, v182
	v_lshlrev_b64 v[182:183], 1, v[182:183]
	v_readfirstlane_b32 s19, v187
	v_lshl_add_u64 v[174:175], s[6:7], 0, v[182:183]
	s_mov_b32 m0, s19
	v_lshl_add_u64 v[176:177], s[0:1], 0, v[176:177]
	global_load_lds_dwordx4 v[174:175], off
	v_subrev_u32_e32 v248, s6, v174
	v_add_u32_e32 v174, 0x8000, v179
	s_nop 0
	v_readfirstlane_b32 s19, v174
	s_mov_b32 m0, s19
	s_nop 0
	global_load_lds_dwordx4 v[176:177], off
	v_subrev_u32_e32 v247, s0, v176
	v_lshl_add_u64 v[176:177], s[0:1], 0, v[180:181]
	v_add_u32_e32 v180, 0xa000, v179
	s_nop 0
	v_readfirstlane_b32 s19, v180
	v_add_u32_e32 v180, 0xc000, v179
	s_mov_b32 m0, s19
	v_readfirstlane_b32 s19, v180
	v_add_u32_e32 v180, 0xe000, v179
	global_load_lds_dwordx4 v[176:177], off
	v_subrev_u32_e32 v246, s0, v176
	v_lshl_add_u64 v[176:177], s[0:1], 0, v[184:185]
	s_mov_b32 m0, s19
	v_readfirstlane_b32 s19, v180
	global_load_lds_dwordx4 v[176:177], off
	v_subrev_u32_e32 v245, s0, v176
	v_lshl_add_u64 v[176:177], s[0:1], 0, v[182:183]
	s_mov_b32 m0, s19
	s_nop 0
	global_load_lds_dwordx4 v[176:177], off
	v_subrev_u32_e32 v244, s0, v176
	s_add_u32 s98, s6, 0x80
	s_addc_u32 s99, s7, 0
	s_add_u32 s100, s0, 0x80
	s_addc_u32 s101, s1, 0
	s_branch .Lg_rot244_main

; #define LDB_(dst, ks) _Pragma("unroll") for (int n = 0; n < 4; ++n) dst[n] = *(const bf16x8*)(sB + b_off + n * 2048 + (ks) * 1024)
; #define LDA_(dst, ks, h) _Pragma("unroll") for (int m = 0; m < 4; ++m) dst[m] = *(const bf16x8*)(sA + a_off + ((h) * 4 + m) * 2048 + (ks) * 1024)
; #define MMA_(A, B, h) _Pragma("unroll") for (int m = 0; m < 4; ++m) _Pragma("unroll") for (int n = 0; n < 4; ++n) \
;       acc[(h) * 4 + m][n] = SWAP ? MFMA16(B[n], A[m], acc[(h) * 4 + m][n]) : MFMA16(A[m], B[n], acc[(h) * 4 + m][n])
; template <int MF, int NF, bool SWAP = true>
; DI void gemm_main(f32x4 (&acc)[MF][NF], const u16* __restrict__ Ab, int lda, const u16* __restrict__ Bb, int ldb,
;                   int K, char* shm) {
;     ...
;   for (int t = 0; t < nt; ++t) {
;     const int cur = RING3 ? cur3 : (t & 1);
;     if constexpr (RING3) {
;       if (t + 2 < nt) G_STAGE(nxt3, t + 2);
;     } else {
;       if (t + 1 < nt) G_STAGE(cur ^ 1, t + 1);
;     ...
;     if constexpr (MF == 8 && NF == 4) {
;       bf16x8 B0[4], B1[4], A0[4], A1[4], A2[4], A3[4];
;     ...
;       LDB_(B0, 0); LDA_(A0, 0, 0);
;       LDA_(A1, 0, 1); MMA_(A0, B0, 0);
;       LDB_(B1, 1); LDA_(A2, 1, 0); MMA_(A1, B0, 1);
;       LDA_(A3, 1, 1); MMA_(A2, B1, 0);
;       MMA_(A3, B1, 1);
;     ...
;       __builtin_amdgcn_sched_group_barrier(0x100, 8, 0);
; #pragma unroll
;       for (int i = 0; i < 4; ++i) { __builtin_amdgcn_sched_group_barrier(0x100, 1, 0); __builtin_amdgcn_sched_group_barrier(0x008, 4, 0); }
; #pragma unroll
;       for (int i = 0; i < 8; ++i) { __builtin_amdgcn_sched_group_barrier(0x100, 1, 0); __builtin_amdgcn_sched_group_barrier(0x008, 2, 0); }
; #pragma unroll
;       for (int i = 0; i < 4; ++i) { __builtin_amdgcn_sched_group_barrier(0x100, 1, 0); __builtin_amdgcn_sched_group_barrier(0x008, 4, 0); }
;       __builtin_amdgcn_sched_group_barrier(0x008, 16, 0);
;       __builtin_amdgcn_sched_barrier(0);
.LBB0_314:
	s_and_b32 s16, s5, 0x10000
	v_add_u32_e32 v138, s16, v136
	v_add_u32_e32 v186, v138, v129
	v_add_u32_e32 v178, v138, v132
	ds_read_b128 v[138:141], v186
	ds_read_b128 v[158:161], v186 offset:2048
	ds_read_b128 v[142:145], v178 offset:32768
	ds_read_b128 v[146:149], v178 offset:34816
	ds_read_b128 v[150:153], v178 offset:36864
	ds_read_b128 v[154:157], v178 offset:38912
	ds_read_b128 v[162:165], v186 offset:4096
	ds_read_b128 v[166:169], v186 offset:6144
	ds_read_b128 v[170:173], v186 offset:8192
	s_cmp_gt_u32 s15, 14
	s_cbranch_scc1 .Lg_rot314_last
	s_cmp_eq_u32 s15, 0
	s_cbranch_scc1 .Lg_rot314_first
	v_mfma_f32_16x16x32_bf16 v[60:63], v[188:191], v[192:195], v[60:63]
	s_xor_b32 s17, s16, 0x10000
	v_add_u32_e32 v179, s17, v128
	v_mfma_f32_16x16x32_bf16 v[56:59], v[188:191], v[196:199], v[56:59]
	s_nop 0
	v_readfirstlane_b32 s17, v179
	s_nop 1
	s_add_u32 m0, s17, 0x0
	v_mfma_f32_16x16x32_bf16 v[52:55], v[188:191], v[212:215], v[52:55]
	global_load_lds_dwordx4 v251, s[98:99]
	s_add_u32 m0, s17, 0x2000
	v_mfma_f32_16x16x32_bf16 v[48:51], v[188:191], v[216:219], v[48:51]
	global_load_lds_dwordx4 v250, s[98:99]
	s_add_u32 m0, s17, 0x4000
	v_mfma_f32_16x16x32_bf16 v[44:47], v[220:223], v[192:195], v[44:47]
	global_load_lds_dwordx4 v249, s[98:99]
	s_add_u32 m0, s17, 0x6000
	v_mfma_f32_16x16x32_bf16 v[40:43], v[220:223], v[196:199], v[40:43]
	global_load_lds_dwordx4 v248, s[98:99]
	s_add_u32 m0, s17, 0x8000
	v_mfma_f32_16x16x32_bf16 v[36:39], v[220:223], v[212:215], v[36:39]
	global_load_lds_dwordx4 v247, s[100:101]
	s_add_u32 m0, s17, 0xa000
	v_mfma_f32_16x16x32_bf16 v[32:35], v[220:223], v[216:219], v[32:35]
	global_load_lds_dwordx4 v246, s[100:101]
	s_add_u32 m0, s17, 0xc000
	v_mfma_f32_16x16x32_bf16 v[28:31], v[224:227], v[192:195], v[28:31]
	global_load_lds_dwordx4 v245, s[100:101]
	s_add_u32 m0, s17, 0xe000
	v_mfma_f32_16x16x32_bf16 v[24:27], v[224:227], v[196:199], v[24:27]
	global_load_lds_dwordx4 v244, s[100:101]
	v_mfma_f32_16x16x32_bf16 v[20:23], v[224:227], v[212:215], v[20:23]
	s_add_u32 s98, s98, 0x80
	s_addc_u32 s99, s99, 0
	s_add_u32 s100, s100, 0x80
	s_addc_u32 s101, s101, 0
	v_mfma_f32_16x16x32_bf16 v[16:19], v[224:227], v[216:219], v[16:19]
	v_mfma_f32_16x16x32_bf16 v[12:15], v[228:231], v[192:195], v[12:15]
	v_mfma_f32_16x16x32_bf16 v[4:7], v[228:231], v[196:199], v[4:7]
	v_mfma_f32_16x16x32_bf16 v[0:3], v[228:231], v[212:215], v[0:3]
	v_mfma_f32_16x16x32_bf16 v[8:11], v[228:231], v[216:219], v[8:11]
	s_branch .Lg_rot314_main
.Lg_rot314_first:
	v_add_u32_e32 v174, s13, v137
	s_xor_b32 s17, s16, 0x10000
	v_add_u32_e32 v176, 64, v174
	v_add_u32_e32 v179, s17, v128
	v_ashrrev_i32_e32 v177, 31, v176
	v_lshlrev_b64 v[176:177], 1, v[176:177]
	v_readfirstlane_b32 s17, v179
	v_lshl_add_u64 v[180:181], s[6:7], 0, v[176:177]
	s_mov_b32 m0, s17
	v_add_u32_e32 v182, 0x2000, v179
	global_load_lds_dwordx4 v[180:181], off
	v_subrev_u32_e32 v251, s6, v180
	v_add_u32_e32 v180, 0x10040, v174
	v_ashrrev_i32_e32 v181, 31, v180
	v_lshlrev_b64 v[180:181], 1, v[180:181]
	v_readfirstlane_b32 s17, v182
	v_lshl_add_u64 v[184:185], s[6:7], 0, v[180:181]
	s_mov_b32 m0, s17
	v_add_u32_e32 v175, 0x4000, v179
	global_load_lds_dwordx4 v[184:185], off
	v_subrev_u32_e32 v250, s6, v184
	v_add_u32_e32 v184, 0x20040, v174
	v_ashrrev_i32_e32 v185, 31, v184
	v_lshlrev_b64 v[184:185], 1, v[184:185]
	v_readfirstlane_b32 s17, v175
	v_lshl_add_u64 v[182:183], s[6:7], 0, v[184:185]
	s_mov_b32 m0, s17
	v_add_u32_e32 v187, 0x6000, v179
	global_load_lds_dwordx4 v[182:183], off
	v_subrev_u32_e32 v249, s6, v182
	v_add_u32_e32 v182, 0x30040, v174
	v_ashrrev_i32_e32 v183, 31, v182
	v_lshlrev_b64 v[182:183], 1, v[182:183]
	v_readfirstlane_b32 s17, v187
	v_lshl_add_u64 v[174:175], s[6:7], 0, v[182:183]
	s_mov_b32 m0, s17
	v_lshl_add_u64 v[176:177], s[0:1], 0, v[176:177]
	global_load_lds_dwordx4 v[174:175], off
	v_subrev_u32_e32 v248, s6, v174
	v_add_u32_e32 v174, 0x8000, v179
	s_nop 0
	v_readfirstlane_b32 s17, v174
	s_mov_b32 m0, s17
	s_nop 0
	global_load_lds_dwordx4 v[176:177], off
	v_subrev_u32_e32 v247, s0, v176
	v_lshl_add_u64 v[176:177], s[0:1], 0, v[180:181]
	v_add_u32_e32 v180, 0xa000, v179
	s_nop 0
	v_readfirstlane_b32 s17, v180
	v_add_u32_e32 v180, 0xc000, v179
	s_mov_b32 m0, s17
	v_readfirstlane_b32 s17, v180
	v_add_u32_e32 v180, 0xe000, v179
	global_load_lds_dwordx4 v[176:177], off
	v_subrev_u32_e32 v246, s0, v176
	v_lshl_add_u64 v[176:177], s[0:1], 0, v[184:185]
	s_mov_b32 m0, s17
	v_readfirstlane_b32 s17, v180
	global_load_lds_dwordx4 v[176:177], off
	v_subrev_u32_e32 v245, s0, v176
	v_lshl_add_u64 v[176:177], s[0:1], 0, v[182:183]
	s_mov_b32 m0, s17
	s_nop 0
	global_load_lds_dwordx4 v[176:177], off
	v_subrev_u32_e32 v244, s0, v176
	s_add_u32 s98, s6, 0x80
	s_addc_u32 s99, s7, 0
	s_add_u32 s100, s0, 0x80
	s_addc_u32 s101, s1, 0
	s_branch .Lg_rot314_main

; template <int MF, int NF, bool SWAP = true>
; DI void gemm_main(f32x4 (&acc)[MF][NF], const u16* __restrict__ Ab, int lda, const u16* __restrict__ Bb, int ldb,
;                   int K, char* shm) {
;     ...
;   for (int t = 0; t < nt; ++t) {
;     const int cur = RING3 ? cur3 : (t & 1);
;     if constexpr (RING3) {
;       if (t + 2 < nt) G_STAGE(nxt3, t + 2);
;     } else {
;       if (t + 1 < nt) G_STAGE(cur ^ 1, t + 1);
; DI void phase_mla_up(const Params& P, int l, char* shm) {
;     ...
;     const u16* Ab = projC + (size_t)brow * 448;
;     rowscale_prologue(Ab, 448, 256, rs);
;     f32x4 acc[8][4];
;     gemm_main<8, 4>(acc, Ab, 448, W + W_UQ + (size_t)bcol * 256, 256, 256, shm);
.LBB0_553:
	s_and_b32 s21, s18, 0x10000
	v_add_u32_e32 v162, s21, v143
	v_add_u32_e32 v186, v162, v142
	ds_read_b128 v[146:149], v186 offset:32768
	ds_read_b128 v[150:153], v186 offset:34816
	ds_read_b128 v[154:157], v186 offset:36864
	ds_read_b128 v[158:161], v186 offset:38912
	v_add_u32_e32 v194, v162, v141
	ds_read_b128 v[162:165], v194
	ds_read_b128 v[166:169], v194 offset:2048
	ds_read_b128 v[170:173], v194 offset:4096
	ds_read_b128 v[174:177], v194 offset:6144
	ds_read_b128 v[178:181], v194 offset:8192
	s_cmp_gt_u32 s20, 2
	s_cbranch_scc1 .Lg_rot553_last
	s_cmp_eq_u32 s20, 0
	s_cbranch_scc1 .Lg_rot553_first
	v_mfma_f32_16x16x32_bf16 v[60:63], v[196:199], v[212:215], v[60:63]
	s_xor_b32 s22, s21, 0x10000
	v_add_u32_e32 v195, s22, v132
	v_mfma_f32_16x16x32_bf16 v[56:59], v[216:219], v[212:215], v[56:59]
	s_nop 0
	v_readfirstlane_b32 s22, v195
	s_nop 1
	s_add_u32 m0, s22, 0x0
	v_mfma_f32_16x16x32_bf16 v[52:55], v[220:223], v[212:215], v[52:55]
	global_load_lds_dwordx4 v251, s[98:99]
	s_add_u32 m0, s22, 0x2000
	v_mfma_f32_16x16x32_bf16 v[48:51], v[224:227], v[212:215], v[48:51]
	global_load_lds_dwordx4 v250, s[98:99]
	s_add_u32 m0, s22, 0x4000
	v_mfma_f32_16x16x32_bf16 v[44:47], v[196:199], v[228:231], v[44:47]
	global_load_lds_dwordx4 v249, s[98:99]
	s_add_u32 m0, s22, 0x6000
	v_mfma_f32_16x16x32_bf16 v[40:43], v[216:219], v[228:231], v[40:43]
	global_load_lds_dwordx4 v248, s[98:99]
	s_add_u32 m0, s22, 0x8000
	v_mfma_f32_16x16x32_bf16 v[36:39], v[220:223], v[228:231], v[36:39]
	global_load_lds_dwordx4 v247, s[100:101]
	s_add_u32 m0, s22, 0xa000
	v_mfma_f32_16x16x32_bf16 v[32:35], v[224:227], v[228:231], v[32:35]
	global_load_lds_dwordx4 v246, s[100:101]
	s_add_u32 m0, s22, 0xc000
	v_mfma_f32_16x16x32_bf16 v[28:31], v[196:199], v[232:235], v[28:31]
	global_load_lds_dwordx4 v245, s[100:101]
	s_add_u32 m0, s22, 0xe000
	v_mfma_f32_16x16x32_bf16 v[24:27], v[216:219], v[232:235], v[24:27]
	global_load_lds_dwordx4 v244, s[100:101]
	v_mfma_f32_16x16x32_bf16 v[20:23], v[220:223], v[232:235], v[20:23]
	s_add_u32 s98, s98, 0x80
	s_addc_u32 s99, s99, 0
	s_add_u32 s100, s100, 0x80
	s_addc_u32 s101, s101, 0
	v_mfma_f32_16x16x32_bf16 v[16:19], v[224:227], v[232:235], v[16:19]
	v_mfma_f32_16x16x32_bf16 v[12:15], v[196:199], v[236:239], v[12:15]
	v_mfma_f32_16x16x32_bf16 v[4:7], v[216:219], v[236:239], v[4:7]
	v_mfma_f32_16x16x32_bf16 v[0:3], v[220:223], v[236:239], v[0:3]
	v_mfma_f32_16x16x32_bf16 v[8:11], v[224:227], v[236:239], v[8:11]
	s_branch .Lg_rot553_main
.Lg_rot553_first:
	s_xor_b32 s22, s21, 0x10000
	v_add_u32_e32 v187, s19, v145
	v_add_u32_e32 v195, s22, v132
	v_add_u32_e32 v182, 64, v187
	v_ashrrev_i32_e32 v183, 31, v182
	v_readfirstlane_b32 s22, v195
	v_lshl_add_u64 v[182:183], v[182:183], 1, s[4:5]
	s_mov_b32 m0, s22
	v_add_u32_e32 v211, 0x2000, v195
	global_load_lds_dwordx4 v[182:183], off
	v_subrev_u32_e32 v251, s4, v182
	v_add_u32_e32 v182, 0x7040, v187
	v_ashrrev_i32_e32 v183, 31, v182
	v_readfirstlane_b32 s22, v211
	v_lshl_add_u64 v[182:183], v[182:183], 1, s[4:5]
	s_mov_b32 m0, s22
	v_add_u32_e32 v211, 0x4000, v195
	global_load_lds_dwordx4 v[182:183], off
	v_subrev_u32_e32 v250, s4, v182
	v_add_u32_e32 v182, 0xe040, v187
	v_ashrrev_i32_e32 v183, 31, v182
	v_readfirstlane_b32 s22, v211
	v_lshl_add_u64 v[182:183], v[182:183], 1, s[4:5]
	s_mov_b32 m0, s22
	v_add_u32_e32 v211, s19, v144
	global_load_lds_dwordx4 v[182:183], off
	v_subrev_u32_e32 v249, s4, v182
	v_add_u32_e32 v182, 0x15040, v187
	v_add_u32_e32 v187, 0x6000, v195
	v_ashrrev_i32_e32 v183, 31, v182
	v_readfirstlane_b32 s22, v187
	v_lshl_add_u64 v[182:183], v[182:183], 1, s[4:5]
	s_mov_b32 m0, s22
	v_add_u32_e32 v187, 0x8000, v195
	global_load_lds_dwordx4 v[182:183], off
	v_subrev_u32_e32 v248, s4, v182
	v_add_u32_e32 v182, 64, v211
	v_ashrrev_i32_e32 v183, 31, v182
	v_readfirstlane_b32 s22, v187
	v_lshl_add_u64 v[182:183], v[182:183], 1, s[6:7]
	s_mov_b32 m0, s22
	v_add_u32_e32 v187, 0xa000, v195
	global_load_lds_dwordx4 v[182:183], off
	v_subrev_u32_e32 v247, s6, v182
	v_add_u32_e32 v182, 0x4040, v211
	v_ashrrev_i32_e32 v183, 31, v182
	v_readfirstlane_b32 s22, v187
	v_lshl_add_u64 v[182:183], v[182:183], 1, s[6:7]
	s_mov_b32 m0, s22
	v_add_u32_e32 v187, 0xc000, v195
	global_load_lds_dwordx4 v[182:183], off
	v_subrev_u32_e32 v246, s6, v182
	v_add_u32_e32 v182, 0x8040, v211
	v_ashrrev_i32_e32 v183, 31, v182
	v_readfirstlane_b32 s22, v187
	v_lshl_add_u64 v[182:183], v[182:183], 1, s[6:7]
	s_mov_b32 m0, s22
	v_add_u32_e32 v195, 0xe000, v195
	global_load_lds_dwordx4 v[182:183], off
	v_subrev_u32_e32 v245, s6, v182
	v_add_u32_e32 v182, 0xc040, v211
	v_ashrrev_i32_e32 v183, 31, v182
	v_readfirstlane_b32 s22, v195
	v_lshl_add_u64 v[182:183], v[182:183], 1, s[6:7]
	s_mov_b32 m0, s22
	s_nop 0
	global_load_lds_dwordx4 v[182:183], off
	v_subrev_u32_e32 v244, s6, v182
	s_add_u32 s98, s4, 0x80
	s_addc_u32 s99, s5, 0
	s_add_u32 s100, s6, 0x80
	s_addc_u32 s101, s7, 0
	s_branch .Lg_rot553_main

; DI float bflo(unsigned v) { return __uint_as_float(v << 16); }
; DI float bfhi(unsigned v) { return __uint_as_float(v & 0xffff0000u); }
; DI void attn_c_item(const Params& P, int l, int b, int h, int qb, char* shm, float B2, int dry) {
;     ...
;   const int q0 = qb * 256 + wid * 32;
;   bf16x8 qf[2][6];
;   const float qscale = 0.07216878364870323f * 1.4426950408889634f;
; #pragma unroll
;   for (int qs = 0; qs < 2; ++qs) {
;     const int t = b * SEQ + q0 + qs * 16 + fr;
;     const u16* qp = qraw + (size_t)t * 768 + h * 192 + fq * 8;
;     float v[6][8];
;     float ss = 0.f;
; #pragma unroll
;     for (int ks = 0; ks < 6; ++ks) {
;       i32x4 raw = *(const i32x4*)(qp + ks * 32);
; #pragma unroll
;       for (int e = 0; e < 4; ++e) {
;         v[ks][2 * e] = bflo((unsigned)raw[e]);
;         v[ks][2 * e + 1] = bfhi((unsigned)raw[e]);
;         ss += v[ks][2 * e] * v[ks][2 * e] + v[ks][2 * e + 1] * v[ks][2 * e + 1];
;       }
;     }
;     ss += __shfl_xor(ss, 16);
.LBB0_575:
	s_xor_b64 s[20:21], s[0:1], -1
	s_and_b64 s[0:1], s[0:1], exec
	s_cselect_b32 s0, s30, s29
	v_mov_b32_e32 v184, v135
	s_lshl_b32 s35, s0, 8
	s_or_b32 s35, s35, s31
	v_readfirstlane_b32 s1, v184
	v_and_b32_e32 v185, 15, v184
	v_bfe_u32 v16, v184, 4, 2
	s_ashr_i32 s34, s1, 6
	v_or_b32_e32 v0, s35, v185
	v_lshlrev_b32_e32 v132, 4, v16
	v_lshl_add_u32 v114, s34, 5, v0
	v_lshl_add_u64 v[0:1], s[14:15], 0, v[132:133]
	v_mad_i64_i32 v[12:13], s[36:37], v114, s3, v[0:1]
	v_or_b32_e32 v112, 16, v114
	global_load_dwordx4 v[50:53], v[12:13], off offset:256
	global_load_dwordx4 v[64:67], v[12:13], off offset:320
	v_mad_i64_i32 v[14:15], s[36:37], v112, s3, v[0:1]
	v_mov_b32_e32 v1, v133
	v_lshlrev_b32_e32 v0, 6, v16
	v_ashrrev_i32_e32 v115, 31, v114
	v_lshl_add_u64 v[0:1], s[10:11], 0, v[0:1]
	v_lshlrev_b64 v[2:3], 8, v[114:115]
	v_lshl_add_u64 v[32:33], v[0:1], 0, v[2:3]
	global_load_dwordx4 v[98:101], v[14:15], off offset:256
	global_load_dwordx4 v[106:109], v[14:15], off offset:320
	global_load_dwordx4 v[46:49], v[32:33], off offset:48
	global_load_dwordx4 v[38:41], v[32:33], off offset:32
	v_ashrrev_i32_e32 v113, 31, v112
	v_lshlrev_b64 v[2:3], 8, v[112:113]
	v_lshl_add_u64 v[62:63], v[0:1], 0, v[2:3]
	global_load_dwordx4 v[0:3], v[62:63], off offset:48
	global_load_dwordx4 v[4:7], v[62:63], off offset:32
	global_load_dwordx4 v[34:37], v[32:33], off offset:16
	global_load_dwordx4 v[8:11], v[62:63], off offset:16
	v_lshlrev_b32_e32 v186, 5, v16
	v_lshlrev_b32_e32 v116, 2, v16
	global_load_dwordx4 v[20:23], v186, s[8:9] offset:528
	global_load_dwordx4 v[28:31], v186, s[8:9] offset:512
	global_load_dwordx4 v[16:19], v186, s[8:9] offset:656
	global_load_dwordx4 v[24:27], v186, s[8:9] offset:640
	global_load_dwordx4 v[54:57], v[12:13], off
	global_load_dwordx4 v[68:71], v[12:13], off offset:64
	global_load_dwordx4 v[76:79], v[12:13], off offset:128
	global_load_dwordx4 v[152:155], v[12:13], off offset:192
	global_load_dwordx4 v[58:61], v[14:15], off
	global_load_dwordx4 v[72:75], v[14:15], off offset:64
	global_load_dwordx4 v[80:83], v[14:15], off offset:128
	global_load_dwordx4 v[156:159], v[14:15], off offset:192
	global_load_dwordx4 v[42:45], v[32:33], off
	s_nop 0
	global_load_dwordx4 v[12:15], v[62:63], off
	s_mov_b32 s36, 0x3baaaaab
	s_lshl_b32 s34, s34, 10
	s_mov_b32 m0, s34
	s_lshl_b32 s35, s0, 2
	s_ashr_i32 s1, s1, 7
	s_add_i32 s0, s35, 4
	s_add_i32 s1, s1, s35
	s_waitcnt vmcnt(0) lgkmcnt(0)
	v_and_b32_e32 v33, 0xffff0000, v53
	v_and_b32_e32 v63, 0xffff0000, v67
	v_and_b32_e32 v105, 0xffff0000, v66
	v_lshlrev_b32_e32 v62, 16, v67
	v_and_b32_e32 v103, 0xffff0000, v52
	v_lshlrev_b32_e32 v104, 16, v66
	v_mov_b32_e32 v92, v63
	v_mov_b32_e32 v93, v105
	v_lshlrev_b32_e32 v32, 16, v53
	v_lshlrev_b32_e32 v102, 16, v52
	v_and_b32_e32 v87, 0xffff0000, v101
	v_mov_b32_e32 v66, v33
	v_mov_b32_e32 v67, v103
	v_mov_b32_e32 v90, v62
	v_mov_b32_e32 v91, v104
	v_and_b32_e32 v89, 0xffff0000, v100
	v_pk_mul_f32 v[94:95], v[92:93], v[92:93]
	v_lshlrev_b32_e32 v86, 16, v101
	v_and_b32_e32 v85, 0xffff0000, v109
	v_mov_b32_e32 v52, v32
	v_mov_b32_e32 v53, v102
	v_lshlrev_b32_e32 v88, 16, v100
	v_mov_b32_e32 v118, v46
	v_mov_b32_e32 v119, v48
	v_mov_b32_e32 v48, v47
	v_pk_mul_f32 v[66:67], v[66:67], v[66:67]
	v_mov_b32_e32 v46, v38
	v_mov_b32_e32 v47, v40
	v_mov_b32_e32 v40, v39
	v_mov_b32_e32 v92, v0
	v_mov_b32_e32 v93, v2
	v_mov_b32_e32 v2, v1
	v_pk_fma_f32 v[38:39], v[90:91], v[90:91], v[94:95]
	v_mov_b32_e32 v0, v87
	v_mov_b32_e32 v1, v89
	v_and_b32_e32 v91, 0xffff0000, v108
	v_lshlrev_b32_e32 v84, 16, v109
	v_mov_b32_e32 v96, v86
	v_mov_b32_e32 v97, v88
	v_pk_fma_f32 v[142:143], v[52:53], v[52:53], v[66:67]
	v_pk_mul_f32 v[0:1], v[0:1], v[0:1]
	v_lshlrev_b32_e32 v90, 16, v108
	v_mov_b32_e32 v52, v85
	v_mov_b32_e32 v53, v91
	v_and_b32_e32 v123, 0xffff0000, v51
	v_and_b32_e32 v129, 0xffff0000, v50
	v_pk_fma_f32 v[146:147], v[96:97], v[96:97], v[0:1]
	v_mov_b32_e32 v0, v84
	v_mov_b32_e32 v1, v90
	v_pk_mul_f32 v[52:53], v[52:53], v[52:53]
	v_lshlrev_b32_e32 v122, 16, v51
	v_mov_b32_e32 v126, v34
	v_mov_b32_e32 v127, v36
	v_mov_b32_e32 v36, v35
	v_lshlrev_b32_e32 v128, 16, v50
	v_mov_b32_e32 v34, v123
	v_mov_b32_e32 v35, v129
	v_pk_fma_f32 v[138:139], v[0:1], v[0:1], v[52:53]
	v_mov_b32_e32 v0, v4
	v_mov_b32_e32 v1, v6
	v_mov_b32_e32 v6, v5
	v_and_b32_e32 v125, 0xffff0000, v65
	v_mov_b32_e32 v4, v8
	v_mov_b32_e32 v5, v10
	v_mov_b32_e32 v10, v9
	v_mov_b32_e32 v8, v122
	v_mov_b32_e32 v9, v128
	v_pk_mul_f32 v[34:35], v[34:35], v[34:35]
	v_and_b32_e32 v131, 0xffff0000, v64
	v_lshlrev_b32_e32 v140, 16, v155
	v_and_b32_e32 v141, 0xffff0000, v155
	v_lshlrev_b32_e32 v144, 16, v154
	v_and_b32_e32 v145, 0xffff0000, v154
	v_lshlrev_b32_e32 v108, 16, v157
	v_and_b32_e32 v109, 0xffff0000, v157
	v_lshlrev_b32_e32 v110, 16, v156
	v_and_b32_e32 v111, 0xffff0000, v156
	v_lshlrev_b32_e32 v154, 16, v79
	v_and_b32_e32 v155, 0xffff0000, v79
	v_lshlrev_b32_e32 v120, 16, v83
	v_and_b32_e32 v121, 0xffff0000, v83
	v_lshlrev_b32_e32 v156, 16, v78
	v_and_b32_e32 v157, 0xffff0000, v78
	v_lshlrev_b32_e32 v78, 16, v82
	v_and_b32_e32 v79, 0xffff0000, v82
	v_lshlrev_b32_e32 v82, 16, v81
	v_and_b32_e32 v83, 0xffff0000, v81
	v_and_b32_e32 v163, 0xffff0000, v71
	v_and_b32_e32 v81, 0xffff0000, v75
	v_lshlrev_b32_e32 v124, 16, v65
	v_pk_fma_f32 v[174:175], v[8:9], v[8:9], v[34:35]
	v_lshlrev_b32_e32 v130, 16, v64
	v_mov_b32_e32 v34, v125
	v_mov_b32_e32 v35, v131
	v_mov_b32_e32 v136, v81
	v_mov_b32_e32 v137, v163
	v_mov_b32_e32 v8, v124
	v_mov_b32_e32 v9, v130
	v_pk_mul_f32 v[34:35], v[34:35], v[34:35]
	v_pk_mul_f32 v[190:191], v[136:137], v[136:137]
	v_and_b32_e32 v167, 0xffff0000, v70
; DI float bflo(unsigned v) { return __uint_as_float(v << 16); }
; DI float bfhi(unsigned v) { return __uint_as_float(v & 0xffff0000u); }
; DI void attn_c_item(const Params& P, int l, int b, int h, int qb, char* shm, float B2, int dry) {
;     ...
;     for (int ks = 0; ks < 6; ++ks) {
;       i32x4 raw = *(const i32x4*)(qp + ks * 32);
; #pragma unroll
;       for (int e = 0; e < 4; ++e) {
;         v[ks][2 * e] = bflo((unsigned)raw[e]);
;         v[ks][2 * e + 1] = bfhi((unsigned)raw[e]);
;         ss += v[ks][2 * e] * v[ks][2 * e] + v[ks][2 * e + 1] * v[ks][2 * e + 1];
;       }
;     }
	v_and_b32_e32 v137, 0xffff0000, v74
	v_lshlrev_b32_e32 v96, 16, v99
	v_and_b32_e32 v97, 0xffff0000, v99
	v_lshlrev_b32_e32 v94, 16, v107
	v_and_b32_e32 v95, 0xffff0000, v107
	v_pk_fma_f32 v[34:35], v[8:9], v[8:9], v[34:35]
	v_lshlrev_b32_e32 v8, 16, v98
	v_and_b32_e32 v9, 0xffff0000, v98
	v_lshlrev_b32_e32 v98, 16, v106
	v_and_b32_e32 v99, 0xffff0000, v106
	v_lshlrev_b32_e32 v100, 16, v159
	v_and_b32_e32 v101, 0xffff0000, v159
	v_lshlrev_b32_e32 v106, 16, v158
	v_and_b32_e32 v107, 0xffff0000, v158
	v_lshlrev_b32_e32 v158, 16, v77
	v_and_b32_e32 v159, 0xffff0000, v77
	v_lshlrev_b32_e32 v160, 16, v76
	v_and_b32_e32 v161, 0xffff0000, v76
	v_lshlrev_b32_e32 v76, 16, v80
	v_and_b32_e32 v77, 0xffff0000, v80
	v_lshlrev_b32_e32 v80, 16, v75
	v_lshlrev_b32_e32 v166, 16, v70
	v_lshlrev_b32_e32 v136, 16, v74
	v_mov_b32_e32 v74, v137
	v_mov_b32_e32 v75, v167
	v_lshlrev_b32_e32 v162, 16, v71
	v_mov_b32_e32 v70, v136
	v_mov_b32_e32 v71, v166
	v_pk_mul_f32 v[74:75], v[74:75], v[74:75]
	v_lshlrev_b32_e32 v148, 16, v153
	v_pk_fma_f32 v[192:193], v[70:71], v[70:71], v[74:75]
	v_and_b32_e32 v71, 0xffff0000, v69
	v_and_b32_e32 v75, 0xffff0000, v73
	v_and_b32_e32 v149, 0xffff0000, v153
	v_lshlrev_b32_e32 v70, 16, v69
	v_lshlrev_b32_e32 v74, 16, v73
	v_and_b32_e32 v171, 0xffff0000, v68
	v_and_b32_e32 v153, 0xffff0000, v72
	v_lshlrev_b32_e32 v178, 16, v55
	v_and_b32_e32 v179, 0xffff0000, v55
	v_lshlrev_b32_e32 v168, 16, v59
	v_and_b32_e32 v169, 0xffff0000, v59
	v_lshlrev_b32_e32 v172, 16, v54
	v_and_b32_e32 v173, 0xffff0000, v54
	v_lshlrev_b32_e32 v54, 16, v58
	v_and_b32_e32 v55, 0xffff0000, v58
	v_mov_b32_e32 v58, v75
	v_mov_b32_e32 v59, v71
	v_lshlrev_b32_e32 v150, 16, v152
	v_and_b32_e32 v151, 0xffff0000, v152
	v_lshlrev_b32_e32 v170, 16, v68
	v_lshlrev_b32_e32 v152, 16, v72
	v_lshlrev_b32_e32 v68, 16, v57
	v_and_b32_e32 v69, 0xffff0000, v57
	v_lshlrev_b32_e32 v72, 16, v61
	v_and_b32_e32 v73, 0xffff0000, v61
	v_lshlrev_b32_e32 v176, 16, v56
	v_and_b32_e32 v177, 0xffff0000, v56
	v_lshlrev_b32_e32 v164, 16, v60
	v_and_b32_e32 v165, 0xffff0000, v60
	v_mov_b32_e32 v56, v74
	v_mov_b32_e32 v57, v70
	v_pk_mul_f32 v[58:59], v[58:59], v[58:59]
	v_mov_b32_e32 v60, v153
	v_mov_b32_e32 v61, v171
	v_pk_fma_f32 v[56:57], v[56:57], v[56:57], v[58:59]
	v_mov_b32_e32 v58, v152
	v_mov_b32_e32 v59, v170
	v_pk_mul_f32 v[60:61], v[60:61], v[60:61]
	v_mov_b32_e32 v194, v73
	v_mov_b32_e32 v195, v69
	v_pk_fma_f32 v[58:59], v[58:59], v[58:59], v[60:61]
	v_mov_b32_e32 v60, v72
	v_mov_b32_e32 v61, v68
	v_pk_mul_f32 v[194:195], v[194:195], v[194:195]
	v_mov_b32_e32 v196, v165
	v_mov_b32_e32 v197, v177
	v_pk_fma_f32 v[60:61], v[60:61], v[60:61], v[194:195]
	v_mov_b32_e32 v194, v164
	v_mov_b32_e32 v195, v176
	v_pk_mul_f32 v[196:197], v[196:197], v[196:197]
	v_mov_b32_e32 v198, v169
	v_mov_b32_e32 v199, v179
	v_pk_fma_f32 v[194:195], v[194:195], v[194:195], v[196:197]
	v_mov_b32_e32 v196, v168
	v_mov_b32_e32 v197, v178
	v_pk_mul_f32 v[198:199], v[198:199], v[198:199]
	v_mov_b32_e32 v200, v55
	v_mov_b32_e32 v201, v173
	v_pk_fma_f32 v[196:197], v[196:197], v[196:197], v[198:199]
	v_mov_b32_e32 v198, v54
	v_mov_b32_e32 v199, v172
	v_pk_mul_f32 v[200:201], v[200:201], v[200:201]
	v_mov_b32_e32 v218, v79
	v_pk_fma_f32 v[198:199], v[198:199], v[198:199], v[200:201]
	v_mov_b32_e32 v200, v121
	v_pk_add_f32 v[196:197], v[198:199], v[196:197]
	v_mov_b32_e32 v198, v111
	v_pk_add_f32 v[194:195], v[194:195], v[196:197]
	v_mov_b32_e32 v196, v109
	v_pk_add_f32 v[60:61], v[60:61], v[194:195]
	v_mov_b32_e32 v194, v107
	v_pk_add_f32 v[58:59], v[58:59], v[60:61]
	v_mov_b32_e32 v60, v101
	v_mov_b32_e32 v61, v141
	v_pk_add_f32 v[56:57], v[56:57], v[58:59]
	v_mov_b32_e32 v58, v100
	v_mov_b32_e32 v59, v140
	v_pk_mul_f32 v[60:61], v[60:61], v[60:61]
	v_mov_b32_e32 v195, v145
	v_pk_fma_f32 v[58:59], v[58:59], v[58:59], v[60:61]
	v_mov_b32_e32 v60, v106
	v_mov_b32_e32 v61, v144
	v_pk_mul_f32 v[194:195], v[194:195], v[194:195]
	v_mov_b32_e32 v197, v149
	v_pk_fma_f32 v[60:61], v[60:61], v[60:61], v[194:195]
	v_mov_b32_e32 v194, v108
	v_mov_b32_e32 v195, v148
	v_pk_mul_f32 v[196:197], v[196:197], v[196:197]
	v_mov_b32_e32 v199, v151
	v_pk_fma_f32 v[194:195], v[194:195], v[194:195], v[196:197]
	v_mov_b32_e32 v196, v110
	v_mov_b32_e32 v197, v150
	v_pk_mul_f32 v[198:199], v[198:199], v[198:199]
	v_mov_b32_e32 v201, v155
	v_pk_fma_f32 v[196:197], v[196:197], v[196:197], v[198:199]
	v_mov_b32_e32 v198, v120
	v_mov_b32_e32 v199, v154
	v_pk_mul_f32 v[200:201], v[200:201], v[200:201]
	v_mov_b32_e32 v219, v157
	v_pk_fma_f32 v[198:199], v[198:199], v[198:199], v[200:201]
	v_mov_b32_e32 v200, v78
	v_mov_b32_e32 v201, v156
	v_pk_mul_f32 v[218:219], v[218:219], v[218:219]
	v_mov_b32_e32 v220, v83
	v_mov_b32_e32 v221, v159
	v_mov_b32_e32 v188, v80
	v_mov_b32_e32 v189, v162
	v_pk_fma_f32 v[200:201], v[200:201], v[200:201], v[218:219]
	v_mov_b32_e32 v218, v82
	v_mov_b32_e32 v219, v158
	v_pk_mul_f32 v[220:221], v[220:221], v[220:221]
	v_mov_b32_e32 v222, v77
	v_mov_b32_e32 v223, v161
	v_mov_b32_e32 v52, v97
	v_mov_b32_e32 v53, v9
	v_pk_fma_f32 v[218:219], v[218:219], v[218:219], v[220:221]
	v_mov_b32_e32 v220, v76
	v_mov_b32_e32 v221, v160
	v_pk_mul_f32 v[222:223], v[222:223], v[222:223]
	v_pk_fma_f32 v[188:189], v[188:189], v[188:189], v[190:191]
	v_pk_add_f32 v[56:57], v[192:193], v[56:57]
	v_mov_b32_e32 v50, v96
	v_mov_b32_e32 v51, v8
	v_pk_mul_f32 v[52:53], v[52:53], v[52:53]
	v_pk_fma_f32 v[220:221], v[220:221], v[220:221], v[222:223]
	v_pk_add_f32 v[56:57], v[188:189], v[56:57]
	v_pk_fma_f32 v[182:183], v[50:51], v[50:51], v[52:53]
	v_mov_b32_e32 v52, v95
	v_mov_b32_e32 v53, v99
	v_pk_add_f32 v[56:57], v[220:221], v[56:57]
; DI void attn_c_item(const Params& P, int l, int b, int h, int qb, char* shm, float B2, int dry) {
;     ...
;     ss += __shfl_xor(ss, 16);
;     ss += __shfl_xor(ss, 32);
;     const float r = rsqrtf(ss * (1.f / 192.f) + EPS);
; #pragma unroll
;     for (int ks = 0; ks < 6; ++ks)
; #pragma unroll
;       for (int e = 0; e < 8; ++e) v[ks][e] *= r * qg[ks * 32 + fq * 8 + e];
;     const f32x4* rt = (const f32x4*)(P.ws + OFF_ROPE) + (size_t)t * 16 + fq * 4;
; #pragma unroll
;     for (int e2 = 0; e2 < 4; ++e2) {
;       const f32x4 cssn = rt[e2];
; #pragma unroll
;       for (int u = 0; u < 2; ++u) {
;         const int e = e2 * 2 + u;
;         const float cs = cssn[2 * u], sn = cssn[2 * u + 1];
;         const float x1 = v[4][e], x2 = v[5][e];
;         v[4][e] = x1 * cs - x2 * sn;
;         v[5][e] = x2 * cs + x1 * sn;
;       }
;     }
; #pragma unroll
;     for (int ks = 0; ks < 6; ++ks) {
;       i32x4 pk;
; #pragma unroll
;       for (int e = 0; e < 4; ++e) pk[e] = (int)pack2(v[ks][2 * e] * qscale, v[ks][2 * e + 1] * qscale);
;       qf[qs][ks] = __builtin_bit_cast(bf16x8, pk);
;     }
	v_mov_b32_e32 v50, v94
	v_mov_b32_e32 v51, v98
	v_pk_mul_f32 v[52:53], v[52:53], v[52:53]
	v_pk_add_f32 v[56:57], v[218:219], v[56:57]
	v_pk_fma_f32 v[180:181], v[50:51], v[50:51], v[52:53]
	global_load_dwordx4 v[50:53], v186, s[8:9] offset:400
	global_load_dwordx4 v[64:67], v186, s[8:9] offset:384
	v_pk_add_f32 v[56:57], v[200:201], v[56:57]
	global_load_dwordx4 v[188:191], v186, s[8:9] offset:256
	v_pk_add_f32 v[56:57], v[198:199], v[56:57]
	s_nop 0
	v_pk_add_f32 v[56:57], v[196:197], v[56:57]
	s_nop 0
	v_pk_add_f32 v[56:57], v[194:195], v[56:57]
	s_nop 0
	v_pk_add_f32 v[56:57], v[60:61], v[56:57]
	s_nop 0
	v_pk_add_f32 v[56:57], v[58:59], v[56:57]
	v_mov_b32_e32 v58, v183
	v_mov_b32_e32 v59, v175
	v_pk_add_f32 v[56:57], v[58:59], v[56:57]
	v_mov_b32_e32 v183, v174
	v_pk_add_f32 v[56:57], v[182:183], v[56:57]
	v_mov_b32_e32 v58, v147
	v_mov_b32_e32 v59, v143
	v_pk_add_f32 v[56:57], v[58:59], v[56:57]
	v_mov_b32_e32 v147, v142
	v_pk_add_f32 v[56:57], v[146:147], v[56:57]
	v_mov_b32_e32 v58, v181
	v_mov_b32_e32 v59, v35
	v_pk_add_f32 v[56:57], v[58:59], v[56:57]
	v_mov_b32_e32 v181, v34
	v_pk_add_f32 v[34:35], v[180:181], v[56:57]
	global_load_dwordx4 v[180:183], v186, s[8:9] offset:272
	global_load_dwordx4 v[192:195], v186, s[8:9] offset:144
	global_load_dwordx4 v[196:199], v186, s[8:9] offset:128
	global_load_dwordx4 v[218:221], v186, s[8:9] offset:16
	global_load_dwordx4 v[222:225], v186, s[8:9]
	v_mov_b32_e32 v56, v139
	v_mov_b32_e32 v57, v39
	v_pk_add_f32 v[34:35], v[56:57], v[34:35]
	v_mov_b32_e32 v139, v38
	v_pk_add_f32 v[34:35], v[138:139], v[34:35]
	ds_bpermute_b32 v39, v212, v35
	ds_bpermute_b32 v38, v212, v34
	v_mov_b32_e32 v56, v42
	v_mov_b32_e32 v57, v44
	v_mov_b32_e32 v44, v43
	v_mov_b32_e32 v42, v12
	s_waitcnt lgkmcnt(0)
	v_pk_add_f32 v[34:35], v[34:35], v[38:39]
	ds_bpermute_b32 v39, v211, v35
	ds_bpermute_b32 v38, v211, v34
	v_mov_b32_e32 v43, v14
	v_mov_b32_e32 v14, v13
	s_waitcnt lgkmcnt(0)
	v_pk_add_f32 v[12:13], v[34:35], v[38:39]
	s_nop 0
	v_pk_fma_f32 v[12:13], v[12:13], s[36:37], v[134:135] op_sel_hi:[1,0,0]
	s_mov_b32 s36, 0
	v_mul_f32_e32 v34, 0x4b800000, v13
	v_cmp_gt_f32_e32 vcc, s33, v13
	s_nop 1
	v_cndmask_b32_e32 v13, v13, v34, vcc
	v_rsq_f32_e32 v13, v13
	s_nop 0
	v_mul_f32_e32 v34, 0x45800000, v13
	v_cndmask_b32_e32 v138, v13, v34, vcc
	v_pk_mul_f32 v[34:35], v[138:139], v[22:23] op_sel_hi:[0,1]
	v_pk_mul_f32 v[32:33], v[34:35], v[32:33]
	v_pk_mul_f32 v[34:35], v[138:139], v[18:19] op_sel_hi:[0,1]
	v_pk_mul_f32 v[34:35], v[34:35], v[62:63]
	v_mul_f32_e32 v13, 0x4b800000, v12
	v_pk_mul_f32 v[38:39], v[34:35], v[118:119]
	v_pk_mul_f32 v[34:35], v[34:35], v[48:49]
	v_pk_fma_f32 v[38:39], v[32:33], v[48:49], v[38:39]
	v_pk_fma_f32 v[32:33], v[32:33], v[118:119], v[34:35] neg_lo:[0,0,1] neg_hi:[0,0,1]
	v_pk_mul_f32 v[48:49], v[138:139], v[16:17] op_sel_hi:[0,1]
	v_pk_mul_f32 v[32:33], v[32:33], s[92:93] op_sel_hi:[1,0]
	v_pk_mul_f32 v[48:49], v[48:49], v[104:105]
	v_cvt_pk_bf16_f32 v35, v32, v33
	v_pk_mul_f32 v[32:33], v[38:39], s[92:93] op_sel_hi:[1,0]
	v_pk_mul_f32 v[58:59], v[48:49], v[46:47]
	v_cvt_pk_bf16_f32 v39, v32, v33
	v_pk_mul_f32 v[32:33], v[138:139], v[20:21] op_sel_hi:[0,1]
	v_pk_mul_f32 v[32:33], v[32:33], v[102:103]
	v_cmp_gt_f32_e32 vcc, s33, v12
	v_pk_fma_f32 v[58:59], v[32:33], v[40:41], v[58:59]
	v_pk_mul_f32 v[40:41], v[48:49], v[40:41]
	v_cndmask_b32_e32 v12, v12, v13, vcc
	v_pk_fma_f32 v[32:33], v[32:33], v[46:47], v[40:41] neg_lo:[0,0,1] neg_hi:[0,0,1]
	v_pk_mul_f32 v[40:41], v[138:139], v[26:27] op_sel_hi:[0,1]
	v_pk_mul_f32 v[32:33], v[32:33], s[92:93] op_sel_hi:[1,0]
	v_pk_mul_f32 v[40:41], v[40:41], v[124:125]
	v_cvt_pk_bf16_f32 v34, v32, v33
	v_pk_mul_f32 v[32:33], v[58:59], s[92:93] op_sel_hi:[1,0]
	v_pk_mul_f32 v[46:47], v[40:41], v[126:127]
	v_cvt_pk_bf16_f32 v38, v32, v33
	v_pk_mul_f32 v[32:33], v[138:139], v[30:31] op_sel_hi:[0,1]
	v_pk_mul_f32 v[32:33], v[32:33], v[122:123]
	s_nop 0
	v_pk_fma_f32 v[46:47], v[32:33], v[36:37], v[46:47]
	v_pk_mul_f32 v[36:37], v[40:41], v[36:37]
	v_pk_mul_f32 v[40:41], v[138:139], v[28:29] op_sel_hi:[0,1]
	v_pk_fma_f32 v[32:33], v[32:33], v[126:127], v[36:37] neg_lo:[0,0,1] neg_hi:[0,0,1]
	v_pk_mul_f32 v[36:37], v[46:47], s[92:93] op_sel_hi:[1,0]
	v_pk_mul_f32 v[46:47], v[138:139], v[24:25] op_sel_hi:[0,1]
	v_pk_mul_f32 v[46:47], v[46:47], v[130:131]
	v_pk_mul_f32 v[40:41], v[40:41], v[128:129]
	v_pk_mul_f32 v[48:49], v[46:47], v[56:57]
	v_pk_mul_f32 v[32:33], v[32:33], s[92:93] op_sel_hi:[1,0]
	v_pk_fma_f32 v[48:49], v[40:41], v[44:45], v[48:49]
	v_pk_mul_f32 v[44:45], v[46:47], v[44:45]
	v_cvt_pk_bf16_f32 v33, v32, v33
	v_pk_fma_f32 v[40:41], v[40:41], v[56:57], v[44:45] neg_lo:[0,0,1] neg_hi:[0,0,1]
	v_cvt_pk_bf16_f32 v37, v36, v37
	v_pk_mul_f32 v[40:41], v[40:41], s[92:93] op_sel_hi:[1,0]
	s_nop 0
	v_cvt_pk_bf16_f32 v32, v40, v41
	v_pk_mul_f32 v[40:41], v[48:49], s[92:93] op_sel_hi:[1,0]
	v_rsq_f32_e32 v48, v12
	v_cvt_pk_bf16_f32 v36, v40, v41
	s_waitcnt vmcnt(7)
	v_pk_mul_f32 v[40:41], v[138:139], v[52:53] op_sel_hi:[0,1]
	v_pk_mul_f32 v[40:41], v[40:41], v[140:141]
	s_nop 0
	v_pk_mul_f32 v[40:41], v[40:41], s[92:93] op_sel_hi:[1,0]
	s_nop 0
	v_cvt_pk_bf16_f32 v47, v40, v41
	v_pk_mul_f32 v[40:41], v[50:51], v[138:139] op_sel_hi:[1,0]
	s_nop 0
	v_pk_mul_f32 v[40:41], v[40:41], v[144:145]
	s_nop 0
	v_pk_mul_f32 v[40:41], v[40:41], s[92:93] op_sel_hi:[1,0]
	s_nop 0
	v_cvt_pk_bf16_f32 v46, v40, v41
	s_waitcnt vmcnt(6)
; DI void attn_c_item(const Params& P, int l, int b, int h, int qb, char* shm, float B2, int dry) {
;     ...
; #pragma unroll
;     for (int ks = 0; ks < 6; ++ks)
; #pragma unroll
;       for (int e = 0; e < 8; ++e) v[ks][e] *= r * qg[ks * 32 + fq * 8 + e];
;     const f32x4* rt = (const f32x4*)(P.ws + OFF_ROPE) + (size_t)t * 16 + fq * 4;
; #pragma unroll
;     for (int e2 = 0; e2 < 4; ++e2) {
;       const f32x4 cssn = rt[e2];
; #pragma unroll
;       for (int u = 0; u < 2; ++u) {
;         const int e = e2 * 2 + u;
;         const float cs = cssn[2 * u], sn = cssn[2 * u + 1];
;         const float x1 = v[4][e], x2 = v[5][e];
;         v[4][e] = x1 * cs - x2 * sn;
;         v[5][e] = x2 * cs + x1 * sn;
;       }
;     }
; #pragma unroll
;     for (int ks = 0; ks < 6; ++ks) {
;       i32x4 pk;
; #pragma unroll
;       for (int e = 0; e < 4; ++e) pk[e] = (int)pack2(v[ks][2 * e] * qscale, v[ks][2 * e + 1] * qscale);
;       qf[qs][ks] = __builtin_bit_cast(bf16x8, pk);
;     }
	v_pk_mul_f32 v[40:41], v[66:67], v[138:139] op_sel_hi:[1,0]
	s_nop 0
	v_pk_mul_f32 v[40:41], v[40:41], v[148:149]
	s_nop 0
	v_pk_mul_f32 v[40:41], v[40:41], s[92:93] op_sel_hi:[1,0]
	s_nop 0
	v_cvt_pk_bf16_f32 v45, v40, v41
	v_pk_mul_f32 v[40:41], v[64:65], v[138:139] op_sel_hi:[1,0]
	s_nop 0
	v_pk_mul_f32 v[40:41], v[40:41], v[150:151]
	s_nop 0
	v_pk_mul_f32 v[40:41], v[40:41], s[92:93] op_sel_hi:[1,0]
	s_nop 0
	v_cvt_pk_bf16_f32 v44, v40, v41
	s_waitcnt vmcnt(4)
	v_pk_mul_f32 v[40:41], v[182:183], v[138:139] op_sel_hi:[1,0]
	s_nop 0
	v_pk_mul_f32 v[40:41], v[40:41], v[154:155]
	s_nop 0
	v_pk_mul_f32 v[40:41], v[40:41], s[92:93] op_sel_hi:[1,0]
	s_nop 0
	v_cvt_pk_bf16_f32 v59, v40, v41
	v_pk_mul_f32 v[40:41], v[180:181], v[138:139] op_sel_hi:[1,0]
	s_nop 0
	v_pk_mul_f32 v[40:41], v[40:41], v[156:157]
	s_nop 0
	v_pk_mul_f32 v[40:41], v[40:41], s[92:93] op_sel_hi:[1,0]
	s_nop 0
	v_cvt_pk_bf16_f32 v58, v40, v41
	v_pk_mul_f32 v[40:41], v[190:191], v[138:139] op_sel_hi:[1,0]
	s_nop 0
	v_pk_mul_f32 v[40:41], v[40:41], v[158:159]
	s_nop 0
	v_pk_mul_f32 v[40:41], v[40:41], s[92:93] op_sel_hi:[1,0]
	s_nop 0
	v_cvt_pk_bf16_f32 v57, v40, v41
	v_pk_mul_f32 v[40:41], v[188:189], v[138:139] op_sel_hi:[1,0]
	s_nop 0
	v_pk_mul_f32 v[40:41], v[40:41], v[160:161]
	s_nop 0
	v_pk_mul_f32 v[40:41], v[40:41], s[92:93] op_sel_hi:[1,0]
	s_nop 0
	v_cvt_pk_bf16_f32 v56, v40, v41
	s_waitcnt vmcnt(3)
	v_pk_mul_f32 v[40:41], v[194:195], v[138:139] op_sel_hi:[1,0]
	s_nop 0
	v_pk_mul_f32 v[40:41], v[40:41], v[162:163]
	s_nop 0
	v_pk_mul_f32 v[40:41], v[40:41], s[92:93] op_sel_hi:[1,0]
	s_nop 0
	v_cvt_pk_bf16_f32 v63, v40, v41
	v_pk_mul_f32 v[40:41], v[192:193], v[138:139] op_sel_hi:[1,0]
	s_nop 0
	v_pk_mul_f32 v[40:41], v[40:41], v[166:167]
	s_nop 0
	v_pk_mul_f32 v[40:41], v[40:41], s[92:93] op_sel_hi:[1,0]
	s_nop 0
	v_cvt_pk_bf16_f32 v62, v40, v41
	s_waitcnt vmcnt(2)
	v_pk_mul_f32 v[40:41], v[198:199], v[138:139] op_sel_hi:[1,0]
	s_nop 0
	v_pk_mul_f32 v[40:41], v[40:41], v[70:71]
	s_nop 0
	v_pk_mul_f32 v[40:41], v[40:41], s[92:93] op_sel_hi:[1,0]
	s_nop 0
	v_cvt_pk_bf16_f32 v61, v40, v41
	v_pk_mul_f32 v[40:41], v[196:197], v[138:139] op_sel_hi:[1,0]
	s_nop 0
	v_pk_mul_f32 v[40:41], v[40:41], v[170:171]
	s_nop 0
	v_pk_mul_f32 v[40:41], v[40:41], s[92:93] op_sel_hi:[1,0]
	s_nop 0
	v_cvt_pk_bf16_f32 v60, v40, v41
	s_waitcnt vmcnt(1)
	v_pk_mul_f32 v[40:41], v[220:221], v[138:139] op_sel_hi:[1,0]
	s_nop 0
	v_pk_mul_f32 v[40:41], v[40:41], v[68:69]
	s_nop 0
	v_pk_mul_f32 v[40:41], v[40:41], s[92:93] op_sel_hi:[1,0]
	s_nop 0
	v_cvt_pk_bf16_f32 v71, v40, v41
	v_pk_mul_f32 v[40:41], v[218:219], v[138:139] op_sel_hi:[1,0]
	s_nop 0
	v_pk_mul_f32 v[40:41], v[40:41], v[176:177]
	s_nop 0
	v_pk_mul_f32 v[40:41], v[40:41], s[92:93] op_sel_hi:[1,0]
	s_nop 0
	v_cvt_pk_bf16_f32 v70, v40, v41
	s_waitcnt vmcnt(0)
	v_pk_mul_f32 v[40:41], v[224:225], v[138:139] op_sel_hi:[1,0]
	s_nop 0
	v_pk_mul_f32 v[40:41], v[40:41], v[178:179]
	s_nop 0
	v_pk_mul_f32 v[40:41], v[40:41], s[92:93] op_sel_hi:[1,0]
	s_nop 0
	v_cvt_pk_bf16_f32 v69, v40, v41
	v_pk_mul_f32 v[40:41], v[222:223], v[138:139] op_sel_hi:[1,0]
	s_nop 0
	v_pk_mul_f32 v[12:13], v[40:41], v[172:173]
	s_nop 0
	v_pk_mul_f32 v[12:13], v[12:13], s[92:93] op_sel_hi:[1,0]
	s_nop 0
	v_cvt_pk_bf16_f32 v68, v12, v13
	v_mul_f32_e32 v12, 0x45800000, v48
	v_cndmask_b32_e32 v12, v48, v12, vcc
	v_pk_mul_f32 v[118:119], v[194:195], v[12:13] op_sel_hi:[1,0]
	v_pk_mul_f32 v[40:41], v[222:223], v[12:13] op_sel_hi:[1,0]
	v_pk_mul_f32 v[118:119], v[118:119], v[80:81]
	v_pk_mul_f32 v[80:81], v[188:189], v[12:13] op_sel_hi:[1,0]
	v_pk_mul_f32 v[102:103], v[220:221], v[12:13] op_sel_hi:[1,0]
	v_pk_mul_f32 v[122:123], v[80:81], v[76:77]
	v_pk_mul_f32 v[76:77], v[190:191], v[12:13] op_sel_hi:[1,0]
	v_pk_mul_f32 v[104:105], v[198:199], v[12:13] op_sel_hi:[1,0]
	v_pk_mul_f32 v[124:125], v[76:77], v[82:83]
	v_pk_mul_f32 v[76:77], v[180:181], v[12:13] op_sel_hi:[1,0]
	v_pk_mul_f32 v[28:29], v[28:29], v[12:13] op_sel_hi:[1,0]
	v_pk_mul_f32 v[16:17], v[16:17], v[12:13] op_sel_hi:[1,0]
	v_pk_mul_f32 v[40:41], v[40:41], v[54:55]
	v_pk_mul_f32 v[48:49], v[224:225], v[12:13] op_sel_hi:[1,0]
	v_pk_mul_f32 v[54:55], v[218:219], v[12:13] op_sel_hi:[1,0]
	v_pk_mul_f32 v[72:73], v[102:103], v[72:73]
	v_pk_mul_f32 v[102:103], v[196:197], v[12:13] op_sel_hi:[1,0]
	v_pk_mul_f32 v[74:75], v[104:105], v[74:75]
	v_pk_mul_f32 v[104:105], v[192:193], v[12:13] op_sel_hi:[1,0]
	v_pk_mul_f32 v[126:127], v[76:77], v[78:79]
	v_pk_mul_f32 v[76:77], v[182:183], v[12:13] op_sel_hi:[1,0]
	v_pk_mul_f32 v[64:65], v[64:65], v[12:13] op_sel_hi:[1,0]
	v_pk_mul_f32 v[66:67], v[66:67], v[12:13] op_sel_hi:[1,0]
	v_pk_mul_f32 v[50:51], v[50:51], v[12:13] op_sel_hi:[1,0]
	v_pk_mul_f32 v[52:53], v[52:53], v[12:13] op_sel_hi:[1,0]
	v_pk_mul_f32 v[8:9], v[28:29], v[8:9]
	v_pk_mul_f32 v[28:29], v[30:31], v[12:13] op_sel_hi:[1,0]
	v_pk_mul_f32 v[20:21], v[20:21], v[12:13] op_sel_hi:[1,0]
	v_pk_mul_f32 v[22:23], v[22:23], v[12:13] op_sel_hi:[1,0]
	v_pk_mul_f32 v[24:25], v[24:25], v[12:13] op_sel_hi:[1,0]
	v_pk_mul_f32 v[26:27], v[26:27], v[12:13] op_sel_hi:[1,0]
	v_pk_mul_f32 v[16:17], v[16:17], v[90:91]
	v_pk_mul_f32 v[12:13], v[18:19], v[12:13] op_sel_hi:[1,0]
	v_pk_mul_f32 v[120:121], v[76:77], v[120:121]
	v_pk_mul_f32 v[20:21], v[20:21], v[88:89]
	v_pk_mul_f32 v[12:13], v[12:13], v[84:85]
	v_pk_mul_f32 v[76:77], v[0:1], v[16:17]
	v_pk_mul_f32 v[48:49], v[48:49], v[168:169]
	v_pk_mul_f32 v[22:23], v[22:23], v[86:87]
	v_pk_mul_f32 v[26:27], v[26:27], v[94:95]
	v_pk_fma_f32 v[94:95], v[6:7], v[20:21], v[76:77]
	v_pk_mul_f32 v[76:77], v[92:93], v[12:13]
	v_pk_mul_f32 v[40:41], v[40:41], s[92:93] op_sel_hi:[1,0]
; DI void attn_c_item(const Params& P, int l, int b, int h, int qb, char* shm, float B2, int dry) {
;     ...
;     for (int ks = 0; ks < 6; ++ks) {
;       i32x4 pk;
; #pragma unroll
;       for (int e = 0; e < 4; ++e) pk[e] = (int)pack2(v[ks][2 * e] * qscale, v[ks][2 * e + 1] * qscale);
;       qf[qs][ks] = __builtin_bit_cast(bf16x8, pk);
;     }
;   }
;   constexpr int KT_B = 24576, VT_B = 16384, BUF_B = KT_B + VT_B;
;   const int ntile = qb * 4 + 4;
;   const int my_last = qb * 4 + (wid >> 1);
;   f32x4 o[8][2];
; #pragma unroll
;   for (int i = 0; i < 8; ++i) { o[i][0] = f32x4{0.f, 0.f, 0.f, 0.f}; o[i][1] = f32x4{0.f, 0.f, 0.f, 0.f}; }
;   float lsum[2] = {0.f, 0.f};
;   int kR[3], kC[3], vR[2], vC[2];
; #pragma unroll
;   for (int i = 0; i < 3; ++i) stage_rc<6>((tid + i * 512) * 16, kR[i], kC[i]);
; #pragma unroll
;   for (int i = 0; i < 2; ++i) stage_rc<2>((tid + i * 512) * 16, vR[i], vC[i]);
;   int pk[3], pv[2];
; #pragma unroll
;   for (int i = 0; i < 3; ++i) pk[i] = kR[i] * 192 + kC[i];
; #pragma unroll
;   for (int i = 0; i < 2; ++i) pv[i] = vR[i] * SEQ + vC[i];
;     ...
;   A_STAGE(0, 0);
;   asm volatile("s_waitcnt vmcnt(0)" ::: "memory");
;   __syncthreads();
	v_pk_mul_f32 v[54:55], v[54:55], v[164:165]
	v_pk_mul_f32 v[28:29], v[28:29], v[96:97]
	v_pk_fma_f32 v[96:97], v[2:3], v[22:23], v[76:77]
	v_cvt_pk_bf16_f32 v76, v40, v41
	v_pk_mul_f32 v[40:41], v[48:49], s[92:93] op_sel_hi:[1,0]
	v_pk_mul_f32 v[102:103], v[102:103], v[152:153]
	v_cvt_pk_bf16_f32 v77, v40, v41
	v_pk_mul_f32 v[40:41], v[54:55], s[92:93] op_sel_hi:[1,0]
	v_pk_mul_f32 v[104:105], v[104:105], v[136:137]
	v_cvt_pk_bf16_f32 v78, v40, v41
	v_pk_mul_f32 v[40:41], v[72:73], s[92:93] op_sel_hi:[1,0]
	v_pk_mul_f32 v[24:25], v[24:25], v[98:99]
	v_cvt_pk_bf16_f32 v79, v40, v41
	v_pk_mul_f32 v[40:41], v[102:103], s[92:93] op_sel_hi:[1,0]
	v_pk_mul_f32 v[64:65], v[64:65], v[110:111]
	v_cvt_pk_bf16_f32 v80, v40, v41
	v_pk_mul_f32 v[40:41], v[74:75], s[92:93] op_sel_hi:[1,0]
	v_pk_mul_f32 v[18:19], v[42:43], v[24:25]
	v_cvt_pk_bf16_f32 v81, v40, v41
	v_pk_mul_f32 v[40:41], v[104:105], s[92:93] op_sel_hi:[1,0]
	v_pk_mul_f32 v[66:67], v[66:67], v[108:109]
	v_cvt_pk_bf16_f32 v82, v40, v41
	v_pk_mul_f32 v[40:41], v[118:119], s[92:93] op_sel_hi:[1,0]
	v_pk_fma_f32 v[18:19], v[14:15], v[8:9], v[18:19]
	v_cvt_pk_bf16_f32 v83, v40, v41
	v_pk_mul_f32 v[40:41], v[122:123], s[92:93] op_sel_hi:[1,0]
	v_pk_mul_f32 v[14:15], v[14:15], v[24:25]
	v_cvt_pk_bf16_f32 v84, v40, v41
	v_pk_mul_f32 v[40:41], v[124:125], s[92:93] op_sel_hi:[1,0]
	v_pk_mul_f32 v[50:51], v[50:51], v[106:107]
	v_cvt_pk_bf16_f32 v85, v40, v41
	v_pk_mul_f32 v[40:41], v[126:127], s[92:93] op_sel_hi:[1,0]
	v_pk_fma_f32 v[8:9], v[42:43], v[8:9], v[14:15] neg_lo:[0,0,1] neg_hi:[0,0,1]
	v_cvt_pk_bf16_f32 v86, v40, v41
	v_pk_mul_f32 v[40:41], v[120:121], s[92:93] op_sel_hi:[1,0]
	v_lshlrev_b32_e32 v14, 4, v184
	v_cvt_pk_bf16_f32 v87, v40, v41
	v_pk_mul_f32 v[40:41], v[64:65], s[92:93] op_sel_hi:[1,0]
	v_and_b32_e32 v15, 32, v184
	v_cvt_pk_bf16_f32 v88, v40, v41
	v_pk_mul_f32 v[40:41], v[66:67], s[92:93] op_sel_hi:[1,0]
	v_bitop3_b32 v15, v14, v15, 48 bitop3:0x6c
	v_cvt_pk_bf16_f32 v89, v40, v41
	v_pk_mul_f32 v[40:41], v[50:51], s[92:93] op_sel_hi:[1,0]
	v_bfe_i32 v50, v184, 6, 22
	v_lshrrev_b32_e32 v120, 1, v15
	v_mul_hi_i32 v15, v50, s39
	v_lshrrev_b32_e32 v24, 31, v15
	v_pk_mul_f32 v[52:53], v[52:53], v[100:101]
	v_add_u32_e32 v15, v15, v24
	v_add_u32_e32 v24, 0x2000, v14
	v_cvt_pk_bf16_f32 v90, v40, v41
	v_pk_mul_f32 v[40:41], v[52:53], s[92:93] op_sel_hi:[1,0]
	v_ashrrev_i32_e32 v53, 10, v24
	v_add_u32_e32 v14, 0x4000, v14
	v_cvt_pk_bf16_f32 v91, v40, v41
	v_mul_hi_i32 v40, v53, s39
	v_ashrrev_i32_e32 v64, 10, v14
	v_lshrrev_b32_e32 v41, 31, v40
	v_mul_hi_i32 v14, v64, s39
	v_add_u32_e32 v40, v40, v41
	v_lshrrev_b32_e32 v41, 31, v14
	v_add_u32_e32 v14, v14, v41
	v_bfe_u32 v25, v184, 2, 4
	v_mul_i32_i24_e32 v66, 6, v14
	v_lshl_or_b32 v65, v14, 4, v25
	v_sub_u32_e32 v14, v64, v66
	v_lshl_or_b32 v41, v14, 5, v120
	v_bfe_u32 v14, v184, 27, 1
	v_mul_i32_i24_e32 v52, 6, v15
	v_add_u32_e32 v14, v50, v14
	v_lshl_or_b32 v51, v15, 4, v25
	v_sub_u32_e32 v15, v50, v52
	v_ashrrev_i32_e32 v42, 1, v14
	v_lshrrev_b32_e32 v14, 31, v24
	v_lshl_or_b32 v15, v15, 5, v120
	v_add_u32_e32 v14, v53, v14
	v_mul_i32_i24_e32 v55, 6, v40
	v_ashrrev_i32_e32 v48, 1, v14
	v_mad_i32_i24 v14, v51, s63, v15
	v_lshlrev_b32_e32 v15, 13, v25
	v_lshl_or_b32 v54, v40, 4, v25
	v_sub_u32_e32 v40, v53, v55
	v_mul_i32_i24_e32 v72, 2, v48
	v_lshl_or_b32 v74, v48, 17, v15
	v_lshl_or_b32 v40, v40, 5, v120
	v_mul_i32_i24_e32 v67, 2, v42
	v_sub_u32_e32 v49, v53, v72
	v_lshl_or_b32 v73, v42, 17, v15
	v_or_b32_e32 v15, v74, v120
	v_sub_u32_e32 v43, v50, v67
	v_mad_i32_i24 v24, v54, s63, v40
	v_or_b32_e32 v25, v73, v120
	v_lshl_add_u32 v48, v49, 5, v15
	v_ashrrev_i32_e32 v15, 31, v14
	v_mad_i32_i24 v40, v65, s63, v41
	v_lshl_add_u32 v42, v43, 5, v25
	v_lshl_add_u64 v[14:15], v[14:15], 1, s[12:13]
	v_ashrrev_i32_e32 v25, 31, v24
	global_load_lds_dwordx4 v[14:15], off
	v_lshl_add_u64 v[14:15], v[24:25], 1, s[12:13]
	s_add_i32 m0, s34, 0x2000
	v_ashrrev_i32_e32 v41, 31, v40
	global_load_lds_dwordx4 v[14:15], off
	v_lshl_add_u64 v[14:15], v[40:41], 1, s[12:13]
	s_add_i32 m0, s34, 0x4000
	v_ashrrev_i32_e32 v43, 31, v42
	global_load_lds_dwordx4 v[14:15], off
	s_add_i32 m0, s34, 0x6000
	v_lshl_add_u64 v[14:15], v[42:43], 1, s[16:17]
	v_ashrrev_i32_e32 v49, 31, v48
	global_load_lds_dwordx4 v[14:15], off
	v_lshl_add_u64 v[14:15], v[48:49], 1, s[16:17]
	s_add_i32 m0, s34, 0x8000
	v_pk_mul_f32 v[8:9], v[8:9], s[92:93] op_sel_hi:[1,0]
	global_load_lds_dwordx4 v[14:15], off
	v_cvt_pk_bf16_f32 v100, v8, v9
	v_pk_mul_f32 v[8:9], v[10:11], v[26:27]
	v_pk_mul_f32 v[30:31], v[4:5], v[26:27]
	v_pk_fma_f32 v[4:5], v[4:5], v[28:29], v[8:9] neg_lo:[0,0,1] neg_hi:[0,0,1]
	v_pk_fma_f32 v[30:31], v[10:11], v[28:29], v[30:31]
	v_pk_mul_f32 v[4:5], v[4:5], s[92:93] op_sel_hi:[1,0]
	s_waitcnt vmcnt(0)
	s_waitcnt vmcnt(0) lgkmcnt(0)
	v_cvt_pk_bf16_f32 v101, v4, v5
	v_pk_mul_f32 v[4:5], v[6:7], v[16:17]
	s_barrier
; DI void attn_c_item(const Params& P, int l, int b, int h, int qb, char* shm, float B2, int dry) {
;     ...
;       for (int e = 0; e < 4; ++e) pk[e] = (int)pack2(v[ks][2 * e] * qscale, v[ks][2 * e + 1] * qscale);
;       qf[qs][ks] = __builtin_bit_cast(bf16x8, pk);
;     }
;   }
;   constexpr int KT_B = 24576, VT_B = 16384, BUF_B = KT_B + VT_B;
;   const int ntile = qb * 4 + 4;
;   const int my_last = qb * 4 + (wid >> 1);
;   f32x4 o[8][2];
; #pragma unroll
;   for (int i = 0; i < 8; ++i) { o[i][0] = f32x4{0.f, 0.f, 0.f, 0.f}; o[i][1] = f32x4{0.f, 0.f, 0.f, 0.f}; }
;   float lsum[2] = {0.f, 0.f};
;   int kR[3], kC[3], vR[2], vC[2];
; #pragma unroll
;   for (int i = 0; i < 3; ++i) stage_rc<6>((tid + i * 512) * 16, kR[i], kC[i]);
; #pragma unroll
;   for (int i = 0; i < 2; ++i) stage_rc<2>((tid + i * 512) * 16, vR[i], vC[i]);
;   int pk[3], pv[2];
; #pragma unroll
;   for (int i = 0; i < 3; ++i) pk[i] = kR[i] * 192 + kC[i];
; #pragma unroll
;   for (int i = 0; i < 2; ++i) pv[i] = vR[i] * SEQ + vC[i];
;     ...
;   A_STAGE(0, 0);
;   asm volatile("s_waitcnt vmcnt(0)" ::: "memory");
;   __syncthreads();
; #pragma clang loop unroll(disable)
;   for (int kt = 0; kt < ntile; ++kt) {
;     const int cur = kt & 1;
;     if (kt + 1 < ntile) A_STAGE(cur ^ 1, kt + 1);
;     if (kt <= my_last) {
;       const char* Kb = shm + cur * BUF_B;
;       const char* Vb = Kb + KT_B;
;       f32x4 s[4][2];
; #pragma unroll
;       for (int i = 0; i < 4; ++i) { s[i][0] = f32x4{0.f, 0.f, 0.f, 0.f}; s[i][1] = f32x4{0.f, 0.f, 0.f, 0.f}; }
;       const char* Kf = Kb + lds_byte<6>(fr, fq * 8);
;       const char* Vf = Vb + lds_byte<2>(fr, fq * 8);
	v_pk_fma_f32 v[0:1], v[0:1], v[20:21], v[4:5] neg_lo:[0,0,1] neg_hi:[0,0,1]
	s_nop 0
	v_pk_mul_f32 v[0:1], v[0:1], s[92:93] op_sel_hi:[1,0]
	s_nop 0
	v_cvt_pk_bf16_f32 v102, v0, v1
	v_pk_mul_f32 v[0:1], v[2:3], v[12:13]
	v_lshlrev_b32_e32 v2, 5, v55
	v_pk_fma_f32 v[0:1], v[92:93], v[22:23], v[0:1] neg_lo:[0,0,1] neg_hi:[0,0,1]
	v_lshlrev_b32_e32 v3, 5, v52
	v_pk_mul_f32 v[0:1], v[0:1], s[92:93] op_sel_hi:[1,0]
	s_nop 0
	v_cvt_pk_bf16_f32 v103, v0, v1
	v_pk_mul_f32 v[0:1], v[18:19], s[92:93] op_sel_hi:[1,0]
	s_nop 0
	v_cvt_pk_bf16_f32 v108, v0, v1
	v_pk_mul_f32 v[0:1], v[30:31], s[92:93] op_sel_hi:[1,0]
	s_nop 0
	v_cvt_pk_bf16_f32 v109, v0, v1
	v_pk_mul_f32 v[0:1], v[94:95], s[92:93] op_sel_hi:[1,0]
	s_nop 0
	v_cvt_pk_bf16_f32 v110, v0, v1
	v_pk_mul_f32 v[0:1], v[96:97], s[92:93] op_sel_hi:[1,0]
	s_nop 0
	v_cvt_pk_bf16_f32 v111, v0, v1
	v_lshlrev_b32_e32 v1, 2, v184
	v_lshlrev_b32_e32 v0, 6, v185
	v_and_b32_e32 v1, 32, v1
	v_bitop3_b32 v121, v132, v1, v0 bitop3:0x36
	v_lshlrev_b32_e32 v0, 5, v64
	v_mad_i32_i24 v0, v65, s63, v0
	v_lshlrev_b32_e32 v1, 5, v66
	v_sub_u32_e32 v0, v0, v1
	v_add_u32_e32 v122, 0x3000, v0
	v_lshlrev_b32_e32 v0, 5, v53
	v_mad_i32_i24 v1, v54, s63, v0
	v_sub_u32_e32 v1, v1, v2
	v_add_u32_e32 v123, 0x3000, v1
	v_lshlrev_b32_e32 v1, 5, v50
	v_mad_i32_i24 v2, v51, s63, v1
	v_sub_u32_e32 v2, v2, v3
	v_add_u32_e32 v124, 0x3000, v2
	v_add_u32_e32 v0, v0, v74
	v_lshlrev_b32_e32 v2, 5, v72
	v_sub_u32_e32 v0, v0, v2
	v_add_u32_e32 v125, 64, v0
	v_add_u32_e32 v0, v1, v73
	v_lshlrev_b32_e32 v1, 5, v67
	v_sub_u32_e32 v0, v0, v1
	v_mov_b32_e32 v2, v133
	v_mov_b32_e32 v3, v133
	v_add_u32_e32 v126, 64, v0
	v_mov_b32_e32 v132, v133
	v_mov_b32_e32 v0, v133
	v_mov_b32_e32 v1, v133
	v_mov_b64_e32 v[42:43], v[2:3]
	v_mov_b64_e32 v[6:7], v[2:3]
	v_mov_b64_e32 v[50:51], v[2:3]
	v_mov_b64_e32 v[10:11], v[2:3]
	v_mov_b64_e32 v[54:55], v[2:3]
	v_mov_b64_e32 v[14:15], v[2:3]
	v_mov_b64_e32 v[66:67], v[2:3]
	v_mov_b64_e32 v[18:19], v[2:3]
	v_mov_b64_e32 v[74:75], v[2:3]
	v_mov_b64_e32 v[22:23], v[2:3]
	v_mov_b64_e32 v[94:95], v[2:3]
	v_mov_b64_e32 v[26:27], v[2:3]
	v_mov_b64_e32 v[98:99], v[2:3]
	v_mov_b64_e32 v[30:31], v[2:3]
	v_mov_b64_e32 v[106:107], v[2:3]
	v_mov_b64_e32 v[40:41], v[0:1]
	v_mov_b64_e32 v[4:5], v[0:1]
	v_mov_b64_e32 v[48:49], v[0:1]
	v_mov_b64_e32 v[8:9], v[0:1]
	v_mov_b64_e32 v[52:53], v[0:1]
	v_mov_b64_e32 v[12:13], v[0:1]
	v_mov_b64_e32 v[64:65], v[0:1]
	v_mov_b64_e32 v[16:17], v[0:1]
	v_mov_b64_e32 v[72:73], v[0:1]
	v_mov_b64_e32 v[20:21], v[0:1]
	v_mov_b64_e32 v[92:93], v[0:1]
	v_mov_b64_e32 v[24:25], v[0:1]
	v_mov_b64_e32 v[96:97], v[0:1]
	v_mov_b64_e32 v[28:29], v[0:1]
	v_mov_b64_e32 v[104:105], v[0:1]
	v_mov_b64_e32 v[118:119], v[132:133]
	v_xor_b32_e32 v232, 0x80000000, v117
	v_xor_b32_e32 v233, 0x80000000, v117
	v_xor_b32_e32 v234, 0x80000000, v117
	v_xor_b32_e32 v235, 0x80000000, v117
	s_and_b32 s37, s36, 1
	s_add_i32 s35, s36, 1
	s_cmp_ge_u32 s35, s0
	s_cbranch_scc1 .LBB0_578
	s_branch .LBB0_577

; #define MFMA16(a, b, c) __builtin_amdgcn_mfma_f32_16x16x32_bf16((a), (b), (c), 0, 0, 0)
; DI void attn_c_item(const Params& P, int l, int b, int h, int qb, char* shm, float B2, int dry) {
;     ...
;     if (kt <= my_last) {
;       const char* Kb = shm + cur * BUF_B;
;       const char* Vb = Kb + KT_B;
;       f32x4 s[4][2];
; #pragma unroll
;       for (int i = 0; i < 4; ++i) { s[i][0] = f32x4{0.f, 0.f, 0.f, 0.f}; s[i][1] = f32x4{0.f, 0.f, 0.f, 0.f}; }
;       const char* Kf = Kb + lds_byte<6>(fr, fq * 8);
;       const char* Vf = Vb + lds_byte<2>(fr, fq * 8);
;       bf16x8 kf[2][4], vf0[8], vf1[8];
; #pragma unroll
;       for (int sub = 0; sub < 4; ++sub) kf[0][sub] = *(const bf16x8*)(Kf + sub * 6144);
; #pragma unroll
;       for (int ks = 0; ks < 6; ++ks) {
;         if (ks < 5) {
; #pragma unroll
;           for (int sub = 0; sub < 4; ++sub) kf[(ks + 1) & 1][sub] = *(const bf16x8*)(Kf + sub * 6144 + (ks + 1) * 1024);
;         } else {
; #pragma unroll
;           for (int dvs = 0; dvs < 8; ++dvs) vf0[dvs] = *(const bf16x8*)(Vf + dvs * 2048);
;         }
; #pragma unroll
;         for (int sub = 0; sub < 4; ++sub) {
;           s[sub][0] = MFMA16(kf[ks & 1][sub], qf[0][ks], s[sub][0]);
;           s[sub][1] = MFMA16(kf[ks & 1][sub], qf[1][ks], s[sub][1]);
;         }
;       }
;       __builtin_amdgcn_sched_group_barrier(0x100, 4, 0);
; #pragma unroll
;       for (int i = 0; i < 20; ++i) { __builtin_amdgcn_sched_group_barrier(0x100, 1, 0); __builtin_amdgcn_sched_group_barrier(0x008, 2, 0); }
; #pragma unroll
;       for (int i = 0; i < 4; ++i) { __builtin_amdgcn_sched_group_barrier(0x100, 2, 0); __builtin_amdgcn_sched_group_barrier(0x008, 2, 0); }
;       __builtin_amdgcn_sched_barrier(0);
.LBB0_578:
	s_cmp_gt_i32 s36, s1
	s_cbranch_scc1 .LBB0_580
	s_mul_i32 s37, s37, 0xa000
	v_or_b32_e32 v127, s37, v121
	ds_read_b128 v[128:131], v127
	ds_read_b128 v[136:139], v127 offset:6144
	ds_read_b128 v[140:143], v127 offset:12288
	ds_read_b128 v[144:147], v127 offset:18432
	ds_read_b128 v[148:151], v127 offset:1024
	s_waitcnt lgkmcnt(4)
	v_mfma_f32_16x16x32_bf16 v[152:155], v[128:131], v[68:71], v[232:235]
	v_mfma_f32_16x16x32_bf16 v[128:131], v[128:131], v[76:79], v[232:235]
	ds_read_b128 v[156:159], v127 offset:7168
	s_waitcnt lgkmcnt(4)
	v_mfma_f32_16x16x32_bf16 v[160:163], v[136:139], v[68:71], v[232:235]
	v_mfma_f32_16x16x32_bf16 v[136:139], v[136:139], v[76:79], v[232:235]
	ds_read_b128 v[164:167], v127 offset:13312
	s_waitcnt lgkmcnt(4)
	v_mfma_f32_16x16x32_bf16 v[168:171], v[140:143], v[68:71], v[232:235]
	v_mfma_f32_16x16x32_bf16 v[140:143], v[140:143], v[76:79], v[232:235]
	ds_read_b128 v[172:175], v127 offset:19456
	s_waitcnt lgkmcnt(4)
	v_mfma_f32_16x16x32_bf16 v[176:179], v[144:147], v[68:71], v[232:235]
	v_mfma_f32_16x16x32_bf16 v[144:147], v[144:147], v[76:79], v[232:235]
	ds_read_b128 v[180:183], v127 offset:2048
	s_waitcnt lgkmcnt(4)
	v_mfma_f32_16x16x32_bf16 v[152:155], v[148:151], v[60:63], v[152:155]
	v_mfma_f32_16x16x32_bf16 v[128:131], v[148:151], v[80:83], v[128:131]
	ds_read_b128 v[148:151], v127 offset:8192
	s_waitcnt lgkmcnt(4)
	v_mfma_f32_16x16x32_bf16 v[160:163], v[156:159], v[60:63], v[160:163]
	v_mfma_f32_16x16x32_bf16 v[136:139], v[156:159], v[80:83], v[136:139]
	ds_read_b128 v[156:159], v127 offset:14336
	s_waitcnt lgkmcnt(4)
	v_mfma_f32_16x16x32_bf16 v[168:171], v[164:167], v[60:63], v[168:171]
	v_mfma_f32_16x16x32_bf16 v[140:143], v[164:167], v[80:83], v[140:143]
	ds_read_b128 v[164:167], v127 offset:20480
	s_waitcnt lgkmcnt(4)
	v_mfma_f32_16x16x32_bf16 v[176:179], v[172:175], v[60:63], v[176:179]
	v_mfma_f32_16x16x32_bf16 v[144:147], v[172:175], v[80:83], v[144:147]
	ds_read_b128 v[172:175], v127 offset:3072
	s_waitcnt lgkmcnt(4)
	v_mfma_f32_16x16x32_bf16 v[152:155], v[180:183], v[56:59], v[152:155]
	v_mfma_f32_16x16x32_bf16 v[128:131], v[180:183], v[84:87], v[128:131]
	ds_read_b128 v[180:183], v127 offset:9216
	s_waitcnt lgkmcnt(4)
	v_mfma_f32_16x16x32_bf16 v[160:163], v[148:151], v[56:59], v[160:163]
	v_mfma_f32_16x16x32_bf16 v[136:139], v[148:151], v[84:87], v[136:139]
	ds_read_b128 v[148:151], v127 offset:15360
	s_waitcnt lgkmcnt(4)
	v_mfma_f32_16x16x32_bf16 v[168:171], v[156:159], v[56:59], v[168:171]
	v_mfma_f32_16x16x32_bf16 v[140:143], v[156:159], v[84:87], v[140:143]
	ds_read_b128 v[156:159], v127 offset:21504
	s_waitcnt lgkmcnt(4)
	v_mfma_f32_16x16x32_bf16 v[176:179], v[164:167], v[56:59], v[176:179]
	v_mfma_f32_16x16x32_bf16 v[144:147], v[164:167], v[84:87], v[144:147]
	ds_read_b128 v[164:167], v127 offset:4096
	s_waitcnt lgkmcnt(4)
	v_mfma_f32_16x16x32_bf16 v[152:155], v[172:175], v[44:47], v[152:155]
	v_mfma_f32_16x16x32_bf16 v[128:131], v[172:175], v[88:91], v[128:131]
	ds_read_b128 v[172:175], v127 offset:10240
	s_waitcnt lgkmcnt(4)
	v_mfma_f32_16x16x32_bf16 v[160:163], v[180:183], v[44:47], v[160:163]
	v_mfma_f32_16x16x32_bf16 v[136:139], v[180:183], v[88:91], v[136:139]
	ds_read_b128 v[180:183], v127 offset:16384
	s_waitcnt lgkmcnt(4)
	v_mfma_f32_16x16x32_bf16 v[168:171], v[148:151], v[44:47], v[168:171]
	v_mfma_f32_16x16x32_bf16 v[140:143], v[148:151], v[88:91], v[140:143]
	ds_read_b128 v[148:151], v127 offset:22528
	s_waitcnt lgkmcnt(4)
	v_mfma_f32_16x16x32_bf16 v[176:179], v[156:159], v[44:47], v[176:179]
	v_mfma_f32_16x16x32_bf16 v[144:147], v[156:159], v[88:91], v[144:147]
	ds_read_b128 v[156:159], v127 offset:5120
	s_waitcnt lgkmcnt(4)
	v_mfma_f32_16x16x32_bf16 v[152:155], v[164:167], v[32:35], v[152:155]
	v_mfma_f32_16x16x32_bf16 v[128:131], v[164:167], v[100:103], v[128:131]
	ds_read_b128 v[164:167], v127 offset:11264
	s_waitcnt lgkmcnt(4)
	v_mfma_f32_16x16x32_bf16 v[160:163], v[172:175], v[32:35], v[160:163]
	v_mfma_f32_16x16x32_bf16 v[136:139], v[172:175], v[100:103], v[136:139]
	ds_read_b128 v[172:175], v127 offset:17408
	s_waitcnt lgkmcnt(4)
	v_mfma_f32_16x16x32_bf16 v[168:171], v[180:183], v[32:35], v[168:171]
	v_mfma_f32_16x16x32_bf16 v[140:143], v[180:183], v[100:103], v[140:143]
	ds_read_b128 v[180:183], v127 offset:23552
	s_waitcnt lgkmcnt(4)
	v_mfma_f32_16x16x32_bf16 v[176:179], v[148:151], v[32:35], v[176:179]
	v_mfma_f32_16x16x32_bf16 v[144:147], v[148:151], v[100:103], v[144:147]
	ds_read_b128 v[148:151], v127 offset:38912
	ds_read_b128 v[184:187], v127 offset:36864
	s_waitcnt lgkmcnt(5)
	v_mfma_f32_16x16x32_bf16 v[152:155], v[156:159], v[36:39], v[152:155]
	v_mfma_f32_16x16x32_bf16 v[128:131], v[156:159], v[108:111], v[128:131]
	ds_read_b128 v[156:159], v127 offset:34816
	ds_read_b128 v[188:191], v127 offset:32768
	s_waitcnt lgkmcnt(6)
	v_mfma_f32_16x16x32_bf16 v[160:163], v[164:167], v[36:39], v[160:163]
	v_mfma_f32_16x16x32_bf16 v[136:139], v[164:167], v[108:111], v[136:139]
	ds_read_b128 v[164:167], v127 offset:30720
	ds_read_b128 v[192:195], v127 offset:28672
	s_waitcnt lgkmcnt(7)
	v_mfma_f32_16x16x32_bf16 v[168:171], v[172:175], v[36:39], v[168:171]
	v_mfma_f32_16x16x32_bf16 v[140:143], v[172:175], v[108:111], v[140:143]
	ds_read_b128 v[172:175], v127 offset:26624
	ds_read_b128 v[196:199], v127 offset:24576
	s_waitcnt lgkmcnt(8)
; #define MFMA16(a, b, c) __builtin_amdgcn_mfma_f32_16x16x32_bf16((a), (b), (c), 0, 0, 0)
; DI void attn_c_item(const Params& P, int l, int b, int h, int qb, char* shm, float B2, int dry) {
;     ...
;       bf16x8 pf[2][2];
; #pragma unroll
;       for (int qs = 0; qs < 2; ++qs) {
; #pragma unroll
;         for (int kk = 0; kk < 2; ++kk) {
;           float pv[8];
; #pragma unroll
;           for (int j = 0; j < 4; ++j) {
;             pv[j] = __builtin_amdgcn_exp2f(s[2 * kk][qs][j] - B2);
;             pv[4 + j] = __builtin_amdgcn_exp2f(s[2 * kk + 1][qs][j] - B2);
;           }
;           lsum[qs] += ((pv[0] + pv[1]) + (pv[2] + pv[3])) + ((pv[4] + pv[5]) + (pv[6] + pv[7]));
;           i32x4 pk;
; #pragma unroll
;           for (int e = 0; e < 4; ++e) pk[e] = (int)pack2(pv[2 * e], pv[2 * e + 1]);
;           pf[kk][qs] = __builtin_bit_cast(bf16x8, pk);
;         }
;       }
;       __builtin_amdgcn_sched_barrier(0);
; #pragma unroll
;       for (int dvs = 0; dvs < 8; ++dvs) vf1[dvs] = *(const bf16x8*)(Vf + dvs * 2048 + 1024);
; #pragma unroll
;       for (int dvs = 0; dvs < 8; ++dvs) {
;         o[dvs][0] = MFMA16(vf0[dvs], pf[0][0], o[dvs][0]);
;         o[dvs][1] = MFMA16(vf0[dvs], pf[0][1], o[dvs][1]);
;       }
; #pragma unroll
;       for (int dvs = 0; dvs < 8; ++dvs) {
;         o[dvs][0] = MFMA16(vf1[dvs], pf[1][0], o[dvs][0]);
;         o[dvs][1] = MFMA16(vf1[dvs], pf[1][1], o[dvs][1]);
;       }
; #pragma unroll
;       for (int i = 0; i < 8; ++i) { __builtin_amdgcn_sched_group_barrier(0x100, 1, 0); __builtin_amdgcn_sched_group_barrier(0x008, 2, 0); }
;       __builtin_amdgcn_sched_group_barrier(0x008, 16, 0);
;       __builtin_amdgcn_sched_barrier(0);
	v_mfma_f32_16x16x32_bf16 v[176:179], v[180:183], v[36:39], v[176:179]
	v_mfma_f32_16x16x32_bf16 v[144:147], v[180:183], v[108:111], v[144:147]
	v_exp_f32_e32 v181, v152
	v_exp_f32_e32 v180, v128
	v_exp_f32_e32 v183, v160
	v_exp_f32_e32 v182, v136
	v_exp_f32_e32 v153, v153
	v_exp_f32_e32 v152, v129
	v_exp_f32_e32 v161, v161
	v_exp_f32_e32 v160, v137
	v_exp_f32_e32 v201, v154
	v_exp_f32_e32 v200, v130
	v_exp_f32_e32 v219, v162
	v_exp_f32_e32 v218, v138
	v_exp_f32_e32 v155, v155
	v_exp_f32_e32 v154, v131
	v_exp_f32_e32 v163, v163
	v_exp_f32_e32 v162, v139
	v_exp_f32_e32 v221, v168
	v_exp_f32_e32 v220, v140
	v_exp_f32_e32 v223, v176
	v_exp_f32_e32 v222, v144
	v_exp_f32_e32 v169, v169
	v_exp_f32_e32 v168, v141
	v_exp_f32_e32 v177, v177
	v_exp_f32_e32 v176, v145
	v_exp_f32_e32 v225, v170
	v_exp_f32_e32 v224, v142
	v_exp_f32_e32 v227, v178
	v_exp_f32_e32 v226, v146
	v_exp_f32_e32 v171, v171
	v_exp_f32_e32 v170, v143
	v_pk_add_f32 v[140:141], v[180:181], v[152:153]
	v_pk_add_f32 v[142:143], v[200:201], v[154:155]
	v_exp_f32_e32 v179, v179
	v_exp_f32_e32 v178, v147
	v_pk_add_f32 v[140:141], v[140:141], v[142:143]
	v_pk_add_f32 v[142:143], v[182:183], v[160:161]
	v_pk_add_f32 v[144:145], v[218:219], v[162:163]
	v_cvt_pk_bf16_f32 v128, v181, v153
	v_pk_add_f32 v[142:143], v[142:143], v[144:145]
	v_pk_add_f32 v[144:145], v[226:227], v[178:179]
	v_pk_add_f32 v[140:141], v[140:141], v[142:143]
	v_pk_add_f32 v[142:143], v[224:225], v[170:171]
	v_pk_add_f32 v[118:119], v[118:119], v[140:141]
	v_pk_add_f32 v[140:141], v[220:221], v[168:169]
	v_cvt_pk_bf16_f32 v129, v201, v155
	v_pk_add_f32 v[140:141], v[140:141], v[142:143]
	v_pk_add_f32 v[142:143], v[222:223], v[176:177]
	v_cvt_pk_bf16_f32 v130, v183, v161
	v_pk_add_f32 v[142:143], v[142:143], v[144:145]
	v_cvt_pk_bf16_f32 v131, v219, v163
	v_pk_add_f32 v[228:229], v[140:141], v[142:143]
	v_cvt_pk_bf16_f32 v136, v221, v169
	v_pk_add_f32 v[118:119], v[118:119], v[228:229]
	v_cvt_pk_bf16_f32 v137, v225, v171
	v_cvt_pk_bf16_f32 v138, v223, v177
	v_cvt_pk_bf16_f32 v139, v227, v179
	v_cvt_pk_bf16_f32 v140, v180, v152
	v_cvt_pk_bf16_f32 v141, v200, v154
	v_cvt_pk_bf16_f32 v142, v182, v160
	v_cvt_pk_bf16_f32 v143, v218, v162
	v_cvt_pk_bf16_f32 v144, v220, v168
	v_cvt_pk_bf16_f32 v145, v224, v170
	v_cvt_pk_bf16_f32 v146, v222, v176
	v_cvt_pk_bf16_f32 v147, v226, v178
	ds_read_b128 v[152:155], v127 offset:25600
	s_waitcnt lgkmcnt(1)
	v_mfma_f32_16x16x32_bf16 v[104:107], v[196:199], v[128:131], v[104:107]
	v_mfma_f32_16x16x32_bf16 v[28:31], v[196:199], v[140:143], v[28:31]
	ds_read_b128 v[160:163], v127 offset:27648
	v_mfma_f32_16x16x32_bf16 v[96:99], v[172:175], v[128:131], v[96:99]
	v_mfma_f32_16x16x32_bf16 v[24:27], v[172:175], v[140:143], v[24:27]
	ds_read_b128 v[168:171], v127 offset:29696
	v_mfma_f32_16x16x32_bf16 v[92:95], v[192:195], v[128:131], v[92:95]
	v_mfma_f32_16x16x32_bf16 v[20:23], v[192:195], v[140:143], v[20:23]
	ds_read_b128 v[172:175], v127 offset:31744
	v_mfma_f32_16x16x32_bf16 v[72:75], v[164:167], v[128:131], v[72:75]
	v_mfma_f32_16x16x32_bf16 v[16:19], v[164:167], v[140:143], v[16:19]
	ds_read_b128 v[164:167], v127 offset:33792
	v_mfma_f32_16x16x32_bf16 v[64:67], v[188:191], v[128:131], v[64:67]
	v_mfma_f32_16x16x32_bf16 v[12:15], v[188:191], v[140:143], v[12:15]
	ds_read_b128 v[176:179], v127 offset:35840
	v_mfma_f32_16x16x32_bf16 v[52:55], v[156:159], v[128:131], v[52:55]
	v_mfma_f32_16x16x32_bf16 v[8:11], v[156:159], v[140:143], v[8:11]
	ds_read_b128 v[156:159], v127 offset:37888
	v_mfma_f32_16x16x32_bf16 v[48:51], v[184:187], v[128:131], v[48:51]
	v_mfma_f32_16x16x32_bf16 v[4:7], v[184:187], v[140:143], v[4:7]
	ds_read_b128 v[180:183], v127 offset:39936
	v_mfma_f32_16x16x32_bf16 v[40:43], v[148:151], v[128:131], v[40:43]
	v_mfma_f32_16x16x32_bf16 v[0:3], v[148:151], v[140:143], v[0:3]
	s_waitcnt lgkmcnt(7)
	v_mfma_f32_16x16x32_bf16 v[104:107], v[152:155], v[136:139], v[104:107]
	v_mfma_f32_16x16x32_bf16 v[28:31], v[152:155], v[144:147], v[28:31]
	s_waitcnt lgkmcnt(6)
	v_mfma_f32_16x16x32_bf16 v[96:99], v[160:163], v[136:139], v[96:99]
	v_mfma_f32_16x16x32_bf16 v[24:27], v[160:163], v[144:147], v[24:27]
	s_waitcnt lgkmcnt(5)
	v_mfma_f32_16x16x32_bf16 v[92:95], v[168:171], v[136:139], v[92:95]
	v_mfma_f32_16x16x32_bf16 v[20:23], v[168:171], v[144:147], v[20:23]
	s_waitcnt lgkmcnt(4)
	v_mfma_f32_16x16x32_bf16 v[72:75], v[172:175], v[136:139], v[72:75]
	v_mfma_f32_16x16x32_bf16 v[16:19], v[172:175], v[144:147], v[16:19]
	s_waitcnt lgkmcnt(3)
	v_mfma_f32_16x16x32_bf16 v[64:67], v[164:167], v[136:139], v[64:67]
	v_mfma_f32_16x16x32_bf16 v[12:15], v[164:167], v[144:147], v[12:15]
	s_waitcnt lgkmcnt(2)
	v_mfma_f32_16x16x32_bf16 v[52:55], v[176:179], v[136:139], v[52:55]
	v_mfma_f32_16x16x32_bf16 v[8:11], v[176:179], v[144:147], v[8:11]
	s_waitcnt lgkmcnt(1)
	v_mfma_f32_16x16x32_bf16 v[48:51], v[156:159], v[136:139], v[48:51]
	v_mfma_f32_16x16x32_bf16 v[4:7], v[156:159], v[144:147], v[4:7]
	s_waitcnt lgkmcnt(0)
	v_mfma_f32_16x16x32_bf16 v[40:43], v[180:183], v[136:139], v[40:43]
	v_mfma_f32_16x16x32_bf16 v[0:3], v[180:183], v[144:147], v[0:3]

; #define LDB_(dst, ks) _Pragma("unroll") for (int n = 0; n < 4; ++n) dst[n] = *(const bf16x8*)(sB + b_off + n * 2048 + (ks) * 1024)
; #define LDA_(dst, ks, h) _Pragma("unroll") for (int m = 0; m < 4; ++m) dst[m] = *(const bf16x8*)(sA + a_off + ((h) * 4 + m) * 2048 + (ks) * 1024)
; #define MMA_(A, B, h) _Pragma("unroll") for (int m = 0; m < 4; ++m) _Pragma("unroll") for (int n = 0; n < 4; ++n) \
;       acc[(h) * 4 + m][n] = SWAP ? MFMA16(B[n], A[m], acc[(h) * 4 + m][n]) : MFMA16(A[m], B[n], acc[(h) * 4 + m][n])
; template <int MF, int NF, bool SWAP = true>
; DI void gemm_main(f32x4 (&acc)[MF][NF], const u16* __restrict__ Ab, int lda, const u16* __restrict__ Bb, int ldb,
;                   int K, char* shm) {
;     ...
;   for (int t = 0; t < nt; ++t) {
;     const int cur = RING3 ? cur3 : (t & 1);
;     if constexpr (RING3) {
;       if (t + 2 < nt) G_STAGE(nxt3, t + 2);
;     } else {
;       if (t + 1 < nt) G_STAGE(cur ^ 1, t + 1);
;     }
;     const char* sA = shm + cur * STAGE;
;     const char* sB = sA + TILE_A;
;     if constexpr (MF == 8 && NF == 4) {
;       bf16x8 B0[4], B1[4], A0[4], A1[4], A2[4], A3[4];
;     ...
;       LDB_(B0, 0); LDA_(A0, 0, 0);
;       LDA_(A1, 0, 1); MMA_(A0, B0, 0);
;       LDB_(B1, 1); LDA_(A2, 1, 0); MMA_(A1, B0, 1);
;       LDA_(A3, 1, 1); MMA_(A2, B1, 0);
;       MMA_(A3, B1, 1);
.LBB0_589:
	s_and_b32 s21, s16, 0x10000
	v_add_u32_e32 v137, s21, v132
	v_add_u32_e32 v178, v137, v131
	ds_read_b128 v[138:141], v178 offset:32768
	ds_read_b128 v[142:145], v178 offset:34816
	ds_read_b128 v[146:149], v178 offset:36864
	ds_read_b128 v[150:153], v178 offset:38912
	v_add_u32_e32 v137, v137, v129
	ds_read_b128 v[154:157], v137
	ds_read_b128 v[158:161], v137 offset:2048
	ds_read_b128 v[162:165], v137 offset:4096
	ds_read_b128 v[166:169], v137 offset:6144
	ds_read_b128 v[170:173], v137 offset:8192
	s_cmp_gt_u32 s15, 14
	s_cbranch_scc1 .Lg_rot589_last
	s_cmp_eq_u32 s15, 0
	s_cbranch_scc1 .Lg_rot589_first
	v_mfma_f32_16x16x32_bf16 v[60:63], v[186:189], v[190:193], v[60:63]
	s_xor_b32 s22, s21, 0x10000
	v_add_u32_e32 v179, s22, v128
	v_mfma_f32_16x16x32_bf16 v[56:59], v[194:197], v[190:193], v[56:59]
	s_nop 0
	v_readfirstlane_b32 s22, v179
	s_nop 1
	s_add_u32 m0, s22, 0x0
	v_mfma_f32_16x16x32_bf16 v[52:55], v[198:201], v[190:193], v[52:55]
	global_load_lds_dwordx4 v251, s[98:99]
	s_add_u32 m0, s22, 0x2000
	v_mfma_f32_16x16x32_bf16 v[48:51], v[218:221], v[190:193], v[48:51]
	global_load_lds_dwordx4 v250, s[98:99]
	s_add_u32 m0, s22, 0x4000
	v_mfma_f32_16x16x32_bf16 v[44:47], v[186:189], v[222:225], v[44:47]
	global_load_lds_dwordx4 v249, s[98:99]
	s_add_u32 m0, s22, 0x6000
	v_mfma_f32_16x16x32_bf16 v[40:43], v[194:197], v[222:225], v[40:43]
	global_load_lds_dwordx4 v248, s[98:99]
	s_add_u32 m0, s22, 0x8000
	v_mfma_f32_16x16x32_bf16 v[36:39], v[198:201], v[222:225], v[36:39]
	global_load_lds_dwordx4 v247, s[100:101]
	s_add_u32 m0, s22, 0xa000
	v_mfma_f32_16x16x32_bf16 v[32:35], v[218:221], v[222:225], v[32:35]
	global_load_lds_dwordx4 v246, s[100:101]
	s_add_u32 m0, s22, 0xc000
	v_mfma_f32_16x16x32_bf16 v[28:31], v[186:189], v[226:229], v[28:31]
	global_load_lds_dwordx4 v245, s[100:101]
	s_add_u32 m0, s22, 0xe000
	v_mfma_f32_16x16x32_bf16 v[24:27], v[194:197], v[226:229], v[24:27]
	global_load_lds_dwordx4 v244, s[100:101]
	v_mfma_f32_16x16x32_bf16 v[20:23], v[198:201], v[226:229], v[20:23]
	s_add_u32 s98, s98, 0x80
	s_addc_u32 s99, s99, 0
	s_add_u32 s100, s100, 0x80
	s_addc_u32 s101, s101, 0
	v_mfma_f32_16x16x32_bf16 v[16:19], v[218:221], v[226:229], v[16:19]
	v_mfma_f32_16x16x32_bf16 v[12:15], v[186:189], v[230:233], v[12:15]
	v_mfma_f32_16x16x32_bf16 v[8:11], v[194:197], v[230:233], v[8:11]
	v_mfma_f32_16x16x32_bf16 v[4:7], v[198:201], v[230:233], v[4:7]
	v_mfma_f32_16x16x32_bf16 v[0:3], v[218:221], v[230:233], v[0:3]
	s_branch .Lg_rot589_main
.Lg_rot589_first:
	v_add_u32_e32 v174, s13, v136
	s_xor_b32 s22, s21, 0x10000
	v_add_u32_e32 v176, 64, v174
	v_add_u32_e32 v179, s22, v128
	v_ashrrev_i32_e32 v177, 31, v176
	v_lshlrev_b64 v[176:177], 1, v[176:177]
	v_readfirstlane_b32 s22, v179
	v_lshl_add_u64 v[180:181], s[0:1], 0, v[176:177]
	s_mov_b32 m0, s22
	v_add_u32_e32 v182, 0x2000, v179
	global_load_lds_dwordx4 v[180:181], off
	v_subrev_u32_e32 v251, s0, v180
	v_add_u32_e32 v180, 0x10040, v174
	v_ashrrev_i32_e32 v181, 31, v180
	v_lshlrev_b64 v[180:181], 1, v[180:181]
	v_readfirstlane_b32 s22, v182
	v_lshl_add_u64 v[184:185], s[0:1], 0, v[180:181]
	s_mov_b32 m0, s22
	v_add_u32_e32 v175, 0x4000, v179
	global_load_lds_dwordx4 v[184:185], off
	v_subrev_u32_e32 v250, s0, v184
	v_add_u32_e32 v184, 0x20040, v174
	v_ashrrev_i32_e32 v185, 31, v184
	v_lshlrev_b64 v[184:185], 1, v[184:185]
	v_readfirstlane_b32 s22, v175
	v_lshl_add_u64 v[182:183], s[0:1], 0, v[184:185]
	s_mov_b32 m0, s22
	v_add_u32_e32 v217, 0x6000, v179
	global_load_lds_dwordx4 v[182:183], off
	v_subrev_u32_e32 v249, s0, v182
	v_add_u32_e32 v182, 0x30040, v174
	v_ashrrev_i32_e32 v183, 31, v182
	v_lshlrev_b64 v[182:183], 1, v[182:183]
	v_readfirstlane_b32 s22, v217
	v_lshl_add_u64 v[174:175], s[0:1], 0, v[182:183]
	s_mov_b32 m0, s22
	v_lshl_add_u64 v[176:177], s[4:5], 0, v[176:177]
	global_load_lds_dwordx4 v[174:175], off
	v_subrev_u32_e32 v248, s0, v174
	v_add_u32_e32 v174, 0x8000, v179
	s_nop 0
	v_readfirstlane_b32 s22, v174
	s_mov_b32 m0, s22
	s_nop 0
	global_load_lds_dwordx4 v[176:177], off
	v_subrev_u32_e32 v247, s4, v176
	v_lshl_add_u64 v[176:177], s[4:5], 0, v[180:181]
	v_add_u32_e32 v180, 0xa000, v179
	s_nop 0
	v_readfirstlane_b32 s22, v180
	v_add_u32_e32 v180, 0xc000, v179
	s_mov_b32 m0, s22
	v_readfirstlane_b32 s22, v180
	v_add_u32_e32 v179, 0xe000, v179
	global_load_lds_dwordx4 v[176:177], off
	v_subrev_u32_e32 v246, s4, v176
	v_lshl_add_u64 v[176:177], s[4:5], 0, v[184:185]
	s_mov_b32 m0, s22
	v_readfirstlane_b32 s22, v179
	global_load_lds_dwordx4 v[176:177], off
	v_subrev_u32_e32 v245, s4, v176
	v_lshl_add_u64 v[176:177], s[4:5], 0, v[182:183]
	s_mov_b32 m0, s22
	s_nop 0
	global_load_lds_dwordx4 v[176:177], off
	v_subrev_u32_e32 v244, s4, v176
	s_add_u32 s98, s0, 0x80
	s_addc_u32 s99, s1, 0
	s_add_u32 s100, s4, 0x80
	s_addc_u32 s101, s5, 0
	s_branch .Lg_rot589_main

; #define LDB_(dst, ks) _Pragma("unroll") for (int n = 0; n < 4; ++n) dst[n] = *(const bf16x8*)(sB + b_off + n * 2048 + (ks) * 1024)
; #define LDA_(dst, ks, h) _Pragma("unroll") for (int m = 0; m < 4; ++m) dst[m] = *(const bf16x8*)(sA + a_off + ((h) * 4 + m) * 2048 + (ks) * 1024)
; #define MMA_(A, B, h) _Pragma("unroll") for (int m = 0; m < 4; ++m) _Pragma("unroll") for (int n = 0; n < 4; ++n) \
;       acc[(h) * 4 + m][n] = SWAP ? MFMA16(B[n], A[m], acc[(h) * 4 + m][n]) : MFMA16(A[m], B[n], acc[(h) * 4 + m][n])
; template <int MF, int NF, bool SWAP = true>
; DI void gemm_main(f32x4 (&acc)[MF][NF], const u16* __restrict__ Ab, int lda, const u16* __restrict__ Bb, int ldb,
;                   int K, char* shm) {
;     ...
;   for (int t = 0; t < nt; ++t) {
;     const int cur = RING3 ? cur3 : (t & 1);
;     if constexpr (RING3) {
;       if (t + 2 < nt) G_STAGE(nxt3, t + 2);
;     } else {
;       if (t + 1 < nt) G_STAGE(cur ^ 1, t + 1);
;     }
;     const char* sA = shm + cur * STAGE;
;     const char* sB = sA + TILE_A;
;     if constexpr (MF == 8 && NF == 4) {
;       bf16x8 B0[4], B1[4], A0[4], A1[4], A2[4], A3[4];
;     ...
;       LDB_(B0, 0); LDA_(A0, 0, 0);
;       LDA_(A1, 0, 1); MMA_(A0, B0, 0);
;       LDB_(B1, 1); LDA_(A2, 1, 0); MMA_(A1, B0, 1);
;       LDA_(A3, 1, 1); MMA_(A2, B1, 0);
;       MMA_(A3, B1, 1);
.LBB0_819:
	s_and_b32 s19, s17, 0x10000
	v_add_u32_e32 v137, s19, v132
	v_add_u32_e32 v178, v137, v131
	ds_read_b128 v[138:141], v178 offset:32768
	ds_read_b128 v[142:145], v178 offset:34816
	ds_read_b128 v[146:149], v178 offset:36864
	ds_read_b128 v[150:153], v178 offset:38912
	v_add_u32_e32 v137, v137, v130
	ds_read_b128 v[154:157], v137
	ds_read_b128 v[158:161], v137 offset:2048
	ds_read_b128 v[162:165], v137 offset:4096
	ds_read_b128 v[166:169], v137 offset:6144
	ds_read_b128 v[170:173], v137 offset:8192
	s_cmp_gt_u32 s18, 2
	s_cbranch_scc1 .Lg_rot819_last
	s_cmp_eq_u32 s18, 0
	s_cbranch_scc1 .Lg_rot819_first
	v_mfma_f32_16x16x32_bf16 v[60:63], v[186:189], v[190:193], v[60:63]
	s_xor_b32 s20, s19, 0x10000
	v_add_u32_e32 v179, s20, v129
	v_mfma_f32_16x16x32_bf16 v[56:59], v[194:197], v[190:193], v[56:59]
	s_nop 0
	v_readfirstlane_b32 s20, v179
	s_nop 1
	s_add_u32 m0, s20, 0x0
	v_mfma_f32_16x16x32_bf16 v[52:55], v[198:201], v[190:193], v[52:55]
	global_load_lds_dwordx4 v251, s[98:99]
	s_add_u32 m0, s20, 0x2000
	v_mfma_f32_16x16x32_bf16 v[48:51], v[218:221], v[190:193], v[48:51]
	global_load_lds_dwordx4 v250, s[98:99]
	s_add_u32 m0, s20, 0x4000
	v_mfma_f32_16x16x32_bf16 v[44:47], v[186:189], v[222:225], v[44:47]
	global_load_lds_dwordx4 v249, s[98:99]
	s_add_u32 m0, s20, 0x6000
	v_mfma_f32_16x16x32_bf16 v[40:43], v[194:197], v[222:225], v[40:43]
	global_load_lds_dwordx4 v248, s[98:99]
	s_add_u32 m0, s20, 0x8000
	v_mfma_f32_16x16x32_bf16 v[36:39], v[198:201], v[222:225], v[36:39]
	global_load_lds_dwordx4 v247, s[100:101]
	s_add_u32 m0, s20, 0xa000
	v_mfma_f32_16x16x32_bf16 v[32:35], v[218:221], v[222:225], v[32:35]
	global_load_lds_dwordx4 v246, s[100:101]
	s_add_u32 m0, s20, 0xc000
	v_mfma_f32_16x16x32_bf16 v[28:31], v[186:189], v[226:229], v[28:31]
	global_load_lds_dwordx4 v245, s[100:101]
	s_add_u32 m0, s20, 0xe000
	v_mfma_f32_16x16x32_bf16 v[24:27], v[194:197], v[226:229], v[24:27]
	global_load_lds_dwordx4 v244, s[100:101]
	v_mfma_f32_16x16x32_bf16 v[20:23], v[198:201], v[226:229], v[20:23]
	s_add_u32 s98, s98, 0x80
	s_addc_u32 s99, s99, 0
	s_add_u32 s100, s100, 0x80
	s_addc_u32 s101, s101, 0
	v_mfma_f32_16x16x32_bf16 v[16:19], v[218:221], v[226:229], v[16:19]
	v_mfma_f32_16x16x32_bf16 v[8:11], v[186:189], v[230:233], v[8:11]
	v_mfma_f32_16x16x32_bf16 v[4:7], v[194:197], v[230:233], v[4:7]
	v_mfma_f32_16x16x32_bf16 v[0:3], v[198:201], v[230:233], v[0:3]
	v_mfma_f32_16x16x32_bf16 v[12:15], v[218:221], v[230:233], v[12:15]
	s_branch .Lg_rot819_main
.Lg_rot819_first:
	v_add_u32_e32 v174, s1, v136
	s_xor_b32 s20, s19, 0x10000
	v_add_u32_e32 v176, 64, v174
	v_add_u32_e32 v179, s20, v129
	v_ashrrev_i32_e32 v177, 31, v176
	v_lshlrev_b64 v[176:177], 1, v[176:177]
	v_readfirstlane_b32 s20, v179
	v_lshl_add_u64 v[180:181], s[6:7], 0, v[176:177]
	s_mov_b32 m0, s20
	v_add_u32_e32 v182, 0x2000, v179
	global_load_lds_dwordx4 v[180:181], off
	v_subrev_u32_e32 v251, s6, v180
	v_add_u32_e32 v180, 0x8040, v174
	v_ashrrev_i32_e32 v181, 31, v180
	v_lshlrev_b64 v[180:181], 1, v[180:181]
	v_readfirstlane_b32 s20, v182
	v_lshl_add_u64 v[184:185], s[6:7], 0, v[180:181]
	s_mov_b32 m0, s20
	v_add_u32_e32 v175, 0x4000, v179
	global_load_lds_dwordx4 v[184:185], off
	v_subrev_u32_e32 v250, s6, v184
	v_add_u32_e32 v184, 0x10040, v174
	v_ashrrev_i32_e32 v185, 31, v184
	v_lshlrev_b64 v[184:185], 1, v[184:185]
	v_readfirstlane_b32 s20, v175
	v_lshl_add_u64 v[182:183], s[6:7], 0, v[184:185]
	s_mov_b32 m0, s20
	v_add_u32_e32 v217, 0x6000, v179
	global_load_lds_dwordx4 v[182:183], off
	v_subrev_u32_e32 v249, s6, v182
	v_add_u32_e32 v182, 0x18040, v174
	v_ashrrev_i32_e32 v183, 31, v182
	v_lshlrev_b64 v[182:183], 1, v[182:183]
	v_readfirstlane_b32 s20, v217
	v_lshl_add_u64 v[174:175], s[6:7], 0, v[182:183]
	s_mov_b32 m0, s20
	v_lshl_add_u64 v[176:177], s[8:9], 0, v[176:177]
	global_load_lds_dwordx4 v[174:175], off
	v_subrev_u32_e32 v248, s6, v174
	v_add_u32_e32 v174, 0x8000, v179
	s_nop 0
	v_readfirstlane_b32 s20, v174
	s_mov_b32 m0, s20
	s_nop 0
	global_load_lds_dwordx4 v[176:177], off
	v_subrev_u32_e32 v247, s8, v176
	v_lshl_add_u64 v[176:177], s[8:9], 0, v[180:181]
	v_add_u32_e32 v180, 0xa000, v179
	s_nop 0
	v_readfirstlane_b32 s20, v180
	v_add_u32_e32 v180, 0xc000, v179
	s_mov_b32 m0, s20
	v_readfirstlane_b32 s20, v180
	v_add_u32_e32 v179, 0xe000, v179
	global_load_lds_dwordx4 v[176:177], off
	v_subrev_u32_e32 v246, s8, v176
	v_lshl_add_u64 v[176:177], s[8:9], 0, v[184:185]
	s_mov_b32 m0, s20
	v_readfirstlane_b32 s20, v179
	global_load_lds_dwordx4 v[176:177], off
	v_subrev_u32_e32 v245, s8, v176
	v_lshl_add_u64 v[176:177], s[8:9], 0, v[182:183]
	s_mov_b32 m0, s20
	s_nop 0
	global_load_lds_dwordx4 v[176:177], off
	v_subrev_u32_e32 v244, s8, v176
	s_add_u32 s98, s6, 0x80
	s_addc_u32 s99, s7, 0
	s_add_u32 s100, s8, 0x80
	s_addc_u32 s101, s9, 0
	s_branch .Lg_rot819_main
